# setprio flips removed + leading wave-half skips the lgkmcnt(0) before pre-compute barriers in the 5 large GEMM loops (WAR-safe for that half)
# speedup vs baseline: 1.0151x; 1.0151x over previous
; #define PG8_STAGE(bufoff, gbase, voff) do { _Pragma("unroll") for (int _i = 0; _i < 2; ++_i) { \
;         const unsigned _m0 = ldsu + (unsigned)(bufoff) + ldsw + (unsigned)(_i * 8192); \
;         asm volatile("s_mov_b32 m0, %2\n\ts_nop 0\n\tglobal_load_lds_dwordx4 %0, %1" :: "v"((voff)[_i]), "s"((const char*)(gbase)), "s"(_m0) : "memory"); } } while (0)
; #define PG8_LDA(dst, b, h) do { _Pragma("unroll") for (int m = 0; m < 4; ++m) _Pragma("unroll") for (int k = 0; k < 2; ++k) dst[m][k] = *(const LAS bf16x8*)(lds + PG8_SA(b, h) + aoff + m * 2048 + k * 1024); } while (0)
; #define PG8_LDB(dst, b, h) do { _Pragma("unroll") for (int n = 0; n < 2; ++n) _Pragma("unroll") for (int k = 0; k < 2; ++k) dst[n][k] = *(const LAS bf16x8*)(lds + bbase[b][h] + n * 2048 + k * 1024); } while (0)
; #define PG8_WAIT_V(n) asm volatile("s_waitcnt vmcnt(" #n ")" ::: "memory")
; #define PG8_WAIT_L(n) asm volatile("s_waitcnt lgkmcnt(" #n ")" ::: "memory")
; #define PG8_BAR __builtin_amdgcn_s_barrier()
; #define PG8_SCHED __builtin_amdgcn_sched_barrier(0)
; template <class Epi>
; __device__ __forceinline__ void gemm_phase(LAS unsigned char* lds, const Gemm g, const StaticOrder& S, const Epi& E) {
;     ...
;             PG8_LDB(B0, 0, 0); PG8_SCHED; PG8_LDA(At, 0, 0); PG8_LDA(At2, 0, 1); PG8_STAGE(PG8_SB(1, 1), b1 + hstepB, voffB);
;             PG8_WAIT_V(8); PG8_WAIT_L(0); PG8_BAR; PG8_MMA2B(0, At, At2, B0); PG8_BAR; PG8_SCHED;
;             PG8_LDB(B0, 0, 1); PG8_STAGE(PG8_SB(0, 0), b2, voffB); PG8_STAGE(PG8_SA(0, 0), a2, voffA); PG8_STAGE(PG8_SA(0, 1), a2 + hstepA, voffA);
;             PG8_WAIT_V(8); PG8_WAIT_L(0); PG8_BAR; PG8_MMA2B(1, At, At2, B0); PG8_BAR; PG8_SCHED;
.LBB0_233:
	ds_read_b128 v[130:133], v142
	ds_read_b128 v[148:151], v142 offset:1024
	ds_read_b128 v[152:155], v142 offset:2048
	ds_read_b128 v[156:159], v142 offset:3072
	s_add_u32 s8, s4, 0x100
	s_addc_u32 s9, s5, 0
	s_cmp_eq_u32 s62, 12
	s_cselect_b32 s10, s58, s60
	s_cselect_b32 s11, s15, s61
	s_cselect_b32 s80, s59, s8
	s_cselect_b32 s81, s13, s9
	s_add_u32 s38, s10, 0x80
	s_addc_u32 s39, s11, 0
	ds_read_b128 v[166:169], v143
	ds_read_b128 v[178:181], v143 offset:1024
	ds_read_b128 v[182:185], v143 offset:2048
	ds_read_b128 v[186:189], v143 offset:3072
	ds_read_b128 v[190:193], v143 offset:4096
	ds_read_b128 v[194:197], v143 offset:5120
	ds_read_b128 v[198:201], v143 offset:6144
	ds_read_b128 v[202:205], v143 offset:7168
	ds_read_b128 v[214:217], v143 offset:16384
	ds_read_b128 v[218:221], v143 offset:17408
	ds_read_b128 v[222:225], v143 offset:18432
	ds_read_b128 v[226:229], v143 offset:19456
	ds_read_b128 v[230:233], v143 offset:20480
	ds_read_b128 v[234:237], v143 offset:21504
	ds_read_b128 v[238:241], v143 offset:22528
	ds_read_b128 v[242:245], v143 offset:23552
	s_add_u32 s4, s4, 0x40080
	s_addc_u32 s5, s5, 0
	s_mov_b32 m0, s84
	s_nop 0
	global_load_lds_dwordx4 v137, s[4:5]
	s_mov_b32 m0, s85
	s_nop 0
	global_load_lds_dwordx4 v139, s[4:5]
	s_waitcnt vmcnt(8)
	s_cmp_lg_u64 s[2:3], 0
	s_cbranch_scc1 .Lh0skip_0
	s_waitcnt lgkmcnt(0)
.Lh0skip_0:
	s_barrier
	s_waitcnt lgkmcnt(14)
	v_mfma_f32_16x16x32_bf16 v[124:127], v[130:133], v[166:169], v[124:127]
	v_mfma_f32_16x16x32_bf16 v[120:123], v[152:155], v[166:169], v[120:123]
	s_waitcnt lgkmcnt(13)
	v_mfma_f32_16x16x32_bf16 v[108:111], v[130:133], v[182:185], v[108:111]
	v_mfma_f32_16x16x32_bf16 v[104:107], v[152:155], v[182:185], v[104:107]
	s_waitcnt lgkmcnt(11)
	v_mfma_f32_16x16x32_bf16 v[92:95], v[130:133], v[190:193], v[92:95]
	v_mfma_f32_16x16x32_bf16 v[88:91], v[152:155], v[190:193], v[88:91]
	s_waitcnt lgkmcnt(9)
	v_mfma_f32_16x16x32_bf16 v[76:79], v[130:133], v[198:201], v[76:79]
	v_mfma_f32_16x16x32_bf16 v[72:75], v[152:155], v[198:201], v[72:75]
	s_waitcnt lgkmcnt(7)
	v_mfma_f32_16x16x32_bf16 v[60:63], v[130:133], v[214:217], v[60:63]
	v_mfma_f32_16x16x32_bf16 v[56:59], v[152:155], v[214:217], v[56:59]
	s_waitcnt lgkmcnt(5)
	v_mfma_f32_16x16x32_bf16 v[44:47], v[130:133], v[222:225], v[44:47]
	v_mfma_f32_16x16x32_bf16 v[40:43], v[152:155], v[222:225], v[40:43]
	s_waitcnt lgkmcnt(3)
	v_mfma_f32_16x16x32_bf16 v[28:31], v[130:133], v[230:233], v[28:31]
	v_mfma_f32_16x16x32_bf16 v[24:27], v[152:155], v[230:233], v[24:27]
	s_waitcnt lgkmcnt(1)
	v_mfma_f32_16x16x32_bf16 v[12:15], v[130:133], v[238:241], v[12:15]
	v_mfma_f32_16x16x32_bf16 v[8:11], v[152:155], v[238:241], v[8:11]
	v_mfma_f32_16x16x32_bf16 v[124:127], v[148:151], v[178:181], v[124:127]
	v_mfma_f32_16x16x32_bf16 v[120:123], v[156:159], v[178:181], v[120:123]
	v_mfma_f32_16x16x32_bf16 v[108:111], v[148:151], v[186:189], v[108:111]
	v_mfma_f32_16x16x32_bf16 v[104:107], v[156:159], v[186:189], v[104:107]
	v_mfma_f32_16x16x32_bf16 v[92:95], v[148:151], v[194:197], v[92:95]
	v_mfma_f32_16x16x32_bf16 v[88:91], v[156:159], v[194:197], v[88:91]
	v_mfma_f32_16x16x32_bf16 v[76:79], v[148:151], v[202:205], v[76:79]
	v_mfma_f32_16x16x32_bf16 v[72:75], v[156:159], v[202:205], v[72:75]
	v_mfma_f32_16x16x32_bf16 v[60:63], v[148:151], v[218:221], v[60:63]
	v_mfma_f32_16x16x32_bf16 v[56:59], v[156:159], v[218:221], v[56:59]
	v_mfma_f32_16x16x32_bf16 v[44:47], v[148:151], v[226:229], v[44:47]
	v_mfma_f32_16x16x32_bf16 v[40:43], v[156:159], v[226:229], v[40:43]
	v_mfma_f32_16x16x32_bf16 v[28:31], v[148:151], v[234:237], v[28:31]
	v_mfma_f32_16x16x32_bf16 v[24:27], v[156:159], v[234:237], v[24:27]
	s_waitcnt lgkmcnt(0)
	v_mfma_f32_16x16x32_bf16 v[12:15], v[148:151], v[242:245], v[12:15]
	v_mfma_f32_16x16x32_bf16 v[8:11], v[156:159], v[242:245], v[8:11]
	s_barrier
	ds_read_b128 v[130:133], v144
	ds_read_b128 v[148:151], v144 offset:1024
	ds_read_b128 v[152:155], v144 offset:2048
	ds_read_b128 v[156:159], v144 offset:3072
	s_mov_b32 m0, s29
	s_nop 0
	global_load_lds_dwordx4 v137, s[80:81]
	s_mov_b32 m0, s37
	s_nop 0
	global_load_lds_dwordx4 v139, s[80:81]
	s_mov_b32 m0, s28
	s_nop 0
	global_load_lds_dwordx4 v136, s[10:11]
	s_mov_b32 m0, s47
	s_nop 0
	global_load_lds_dwordx4 v138, s[10:11]
	s_add_u32 s4, s10, 0x40000
	s_addc_u32 s5, s11, 0
	s_mov_b32 m0, s48
	s_nop 0
	global_load_lds_dwordx4 v136, s[4:5]
	s_mov_b32 m0, s49
	s_nop 0
	global_load_lds_dwordx4 v138, s[4:5]
	s_waitcnt vmcnt(8)
	s_cmp_lg_u64 s[2:3], 0
	s_cbranch_scc1 .Lh0skip_1
	s_waitcnt lgkmcnt(0)
; #define PG8_STAGE(bufoff, gbase, voff) do { _Pragma("unroll") for (int _i = 0; _i < 2; ++_i) { \
;         const unsigned _m0 = ldsu + (unsigned)(bufoff) + ldsw + (unsigned)(_i * 8192); \
;         asm volatile("s_mov_b32 m0, %2\n\ts_nop 0\n\tglobal_load_lds_dwordx4 %0, %1" :: "v"((voff)[_i]), "s"((const char*)(gbase)), "s"(_m0) : "memory"); } } while (0)
; #define PG8_LDA(dst, b, h) do { _Pragma("unroll") for (int m = 0; m < 4; ++m) _Pragma("unroll") for (int k = 0; k < 2; ++k) dst[m][k] = *(const LAS bf16x8*)(lds + PG8_SA(b, h) + aoff + m * 2048 + k * 1024); } while (0)
; #define PG8_LDB(dst, b, h) do { _Pragma("unroll") for (int n = 0; n < 2; ++n) _Pragma("unroll") for (int k = 0; k < 2; ++k) dst[n][k] = *(const LAS bf16x8*)(lds + bbase[b][h] + n * 2048 + k * 1024); } while (0)
; #define PG8_WAIT_V(n) asm volatile("s_waitcnt vmcnt(" #n ")" ::: "memory")
; #define PG8_WAIT_L(n) asm volatile("s_waitcnt lgkmcnt(" #n ")" ::: "memory")
; #define PG8_BAR __builtin_amdgcn_s_barrier()
; #define PG8_SCHED __builtin_amdgcn_sched_barrier(0)
; template <class Epi>
; __device__ __forceinline__ void gemm_phase(LAS unsigned char* lds, const Gemm g, const StaticOrder& S, const Epi& E) {
;     ...
;             PG8_WAIT_V(8); PG8_WAIT_L(0); PG8_BAR; PG8_MMA2B(1, At, At2, B0); PG8_BAR; PG8_SCHED;
;             PG8_LDB(B0, 1, 0); PG8_SCHED; PG8_LDA(At, 1, 0); PG8_LDA(At2, 1, 1); PG8_STAGE(PG8_SB(0, 1), b2 + hstepB, voffB);
;             PG8_WAIT_V(8); PG8_WAIT_L(0); PG8_BAR; PG8_MMA2B(0, At, At2, B0); PG8_BAR; PG8_SCHED;
.Lh0skip_1:
	s_barrier
	s_waitcnt lgkmcnt(3)
	v_mfma_f32_16x16x32_bf16 v[116:119], v[130:133], v[166:169], v[116:119]
	s_waitcnt lgkmcnt(1)
	v_mfma_f32_16x16x32_bf16 v[112:115], v[152:155], v[166:169], v[112:115]
	v_mfma_f32_16x16x32_bf16 v[100:103], v[130:133], v[182:185], v[100:103]
	v_mfma_f32_16x16x32_bf16 v[96:99], v[152:155], v[182:185], v[96:99]
	v_mfma_f32_16x16x32_bf16 v[84:87], v[130:133], v[190:193], v[84:87]
	v_mfma_f32_16x16x32_bf16 v[80:83], v[152:155], v[190:193], v[80:83]
	v_mfma_f32_16x16x32_bf16 v[68:71], v[130:133], v[198:201], v[68:71]
	v_mfma_f32_16x16x32_bf16 v[64:67], v[152:155], v[198:201], v[64:67]
	v_mfma_f32_16x16x32_bf16 v[52:55], v[130:133], v[214:217], v[52:55]
	v_mfma_f32_16x16x32_bf16 v[48:51], v[152:155], v[214:217], v[48:51]
	v_mfma_f32_16x16x32_bf16 v[36:39], v[130:133], v[222:225], v[36:39]
	v_mfma_f32_16x16x32_bf16 v[32:35], v[152:155], v[222:225], v[32:35]
	v_mfma_f32_16x16x32_bf16 v[20:23], v[130:133], v[230:233], v[20:23]
	v_mfma_f32_16x16x32_bf16 v[16:19], v[152:155], v[230:233], v[16:19]
	v_mfma_f32_16x16x32_bf16 v[4:7], v[130:133], v[238:241], v[4:7]
	v_mfma_f32_16x16x32_bf16 v[0:3], v[152:155], v[238:241], v[0:3]
	v_mfma_f32_16x16x32_bf16 v[116:119], v[148:151], v[178:181], v[116:119]
	s_waitcnt lgkmcnt(0)
	v_mfma_f32_16x16x32_bf16 v[112:115], v[156:159], v[178:181], v[112:115]
	v_mfma_f32_16x16x32_bf16 v[100:103], v[148:151], v[186:189], v[100:103]
	v_mfma_f32_16x16x32_bf16 v[96:99], v[156:159], v[186:189], v[96:99]
	v_mfma_f32_16x16x32_bf16 v[84:87], v[148:151], v[194:197], v[84:87]
	v_mfma_f32_16x16x32_bf16 v[80:83], v[156:159], v[194:197], v[80:83]
	v_mfma_f32_16x16x32_bf16 v[68:71], v[148:151], v[202:205], v[68:71]
	v_mfma_f32_16x16x32_bf16 v[64:67], v[156:159], v[202:205], v[64:67]
	v_mfma_f32_16x16x32_bf16 v[52:55], v[148:151], v[218:221], v[52:55]
	v_mfma_f32_16x16x32_bf16 v[48:51], v[156:159], v[218:221], v[48:51]
	v_mfma_f32_16x16x32_bf16 v[36:39], v[148:151], v[226:229], v[36:39]
	v_mfma_f32_16x16x32_bf16 v[32:35], v[156:159], v[226:229], v[32:35]
	v_mfma_f32_16x16x32_bf16 v[20:23], v[148:151], v[234:237], v[20:23]
	v_mfma_f32_16x16x32_bf16 v[16:19], v[156:159], v[234:237], v[16:19]
	v_mfma_f32_16x16x32_bf16 v[4:7], v[148:151], v[242:245], v[4:7]
	v_mfma_f32_16x16x32_bf16 v[0:3], v[156:159], v[242:245], v[0:3]
	s_barrier
	ds_read_b128 v[130:133], v145
	ds_read_b128 v[148:151], v145 offset:1024
	ds_read_b128 v[152:155], v145 offset:2048
	ds_read_b128 v[156:159], v145 offset:3072
	ds_read_b128 v[166:169], v143 offset:32768
	ds_read_b128 v[178:181], v143 offset:33792
	ds_read_b128 v[182:185], v143 offset:34816
	ds_read_b128 v[186:189], v143 offset:35840
	ds_read_b128 v[190:193], v143 offset:36864
	ds_read_b128 v[194:197], v143 offset:37888
	ds_read_b128 v[198:201], v143 offset:38912
	ds_read_b128 v[202:205], v143 offset:39936
	ds_read_b128 v[214:217], v143 offset:49152
	ds_read_b128 v[218:221], v143 offset:50176
	ds_read_b128 v[222:225], v143 offset:51200
	ds_read_b128 v[226:229], v143 offset:52224
	ds_read_b128 v[230:233], v143 offset:53248
	ds_read_b128 v[234:237], v143 offset:54272
	ds_read_b128 v[238:241], v143 offset:55296
	ds_read_b128 v[242:245], v143 offset:56320
	s_add_u32 s4, s80, 0x40000
	s_addc_u32 s5, s81, 0
	s_mov_b32 m0, s50
	s_nop 0
	global_load_lds_dwordx4 v137, s[4:5]
	s_mov_b32 m0, s51
	s_nop 0
	global_load_lds_dwordx4 v139, s[4:5]
	s_waitcnt vmcnt(8)
	s_cmp_lg_u64 s[2:3], 0
	s_cbranch_scc1 .Lh0skip_2
	s_waitcnt lgkmcnt(0)
; #define PG8_STAGE(bufoff, gbase, voff) do { _Pragma("unroll") for (int _i = 0; _i < 2; ++_i) { \
;         const unsigned _m0 = ldsu + (unsigned)(bufoff) + ldsw + (unsigned)(_i * 8192); \
;         asm volatile("s_mov_b32 m0, %2\n\ts_nop 0\n\tglobal_load_lds_dwordx4 %0, %1" :: "v"((voff)[_i]), "s"((const char*)(gbase)), "s"(_m0) : "memory"); } } while (0)
; #define PG8_LDB(dst, b, h) do { _Pragma("unroll") for (int n = 0; n < 2; ++n) _Pragma("unroll") for (int k = 0; k < 2; ++k) dst[n][k] = *(const LAS bf16x8*)(lds + bbase[b][h] + n * 2048 + k * 1024); } while (0)
; #define PG8_WAIT_V(n) asm volatile("s_waitcnt vmcnt(" #n ")" ::: "memory")
; #define PG8_WAIT_L(n) asm volatile("s_waitcnt lgkmcnt(" #n ")" ::: "memory")
; #define PG8_BAR __builtin_amdgcn_s_barrier()
; #define PG8_SCHED __builtin_amdgcn_sched_barrier(0)
; template <class Epi>
; __device__ __forceinline__ void gemm_phase(LAS unsigned char* lds, const Gemm g, const StaticOrder& S, const Epi& E) {
;     ...
;             PG8_WAIT_V(8); PG8_WAIT_L(0); PG8_BAR; PG8_MMA2B(0, At, At2, B0); PG8_BAR; PG8_SCHED;
;             PG8_LDB(B0, 1, 1); PG8_STAGE(PG8_SB(1, 0), b3, voffB); PG8_STAGE(PG8_SA(1, 0), a3, voffA); PG8_STAGE(PG8_SA(1, 1), a3 + hstepA, voffA);
;             PG8_WAIT_V(8); PG8_WAIT_L(0); PG8_BAR; PG8_MMA2B(1, At, At2, B0); PG8_BAR; PG8_SCHED;
;         }
.Lh0skip_2:
	s_barrier
	s_waitcnt lgkmcnt(14)
	v_mfma_f32_16x16x32_bf16 v[124:127], v[130:133], v[166:169], v[124:127]
	v_mfma_f32_16x16x32_bf16 v[120:123], v[152:155], v[166:169], v[120:123]
	s_waitcnt lgkmcnt(13)
	v_mfma_f32_16x16x32_bf16 v[108:111], v[130:133], v[182:185], v[108:111]
	v_mfma_f32_16x16x32_bf16 v[104:107], v[152:155], v[182:185], v[104:107]
	s_waitcnt lgkmcnt(11)
	v_mfma_f32_16x16x32_bf16 v[92:95], v[130:133], v[190:193], v[92:95]
	v_mfma_f32_16x16x32_bf16 v[88:91], v[152:155], v[190:193], v[88:91]
	s_waitcnt lgkmcnt(9)
	v_mfma_f32_16x16x32_bf16 v[76:79], v[130:133], v[198:201], v[76:79]
	v_mfma_f32_16x16x32_bf16 v[72:75], v[152:155], v[198:201], v[72:75]
	s_waitcnt lgkmcnt(7)
	v_mfma_f32_16x16x32_bf16 v[60:63], v[130:133], v[214:217], v[60:63]
	v_mfma_f32_16x16x32_bf16 v[56:59], v[152:155], v[214:217], v[56:59]
	s_waitcnt lgkmcnt(5)
	v_mfma_f32_16x16x32_bf16 v[44:47], v[130:133], v[222:225], v[44:47]
	v_mfma_f32_16x16x32_bf16 v[40:43], v[152:155], v[222:225], v[40:43]
	s_waitcnt lgkmcnt(3)
	v_mfma_f32_16x16x32_bf16 v[28:31], v[130:133], v[230:233], v[28:31]
	v_mfma_f32_16x16x32_bf16 v[24:27], v[152:155], v[230:233], v[24:27]
	s_waitcnt lgkmcnt(1)
	v_mfma_f32_16x16x32_bf16 v[12:15], v[130:133], v[238:241], v[12:15]
	v_mfma_f32_16x16x32_bf16 v[8:11], v[152:155], v[238:241], v[8:11]
	v_mfma_f32_16x16x32_bf16 v[124:127], v[148:151], v[178:181], v[124:127]
	v_mfma_f32_16x16x32_bf16 v[120:123], v[156:159], v[178:181], v[120:123]
	v_mfma_f32_16x16x32_bf16 v[108:111], v[148:151], v[186:189], v[108:111]
	v_mfma_f32_16x16x32_bf16 v[104:107], v[156:159], v[186:189], v[104:107]
	v_mfma_f32_16x16x32_bf16 v[92:95], v[148:151], v[194:197], v[92:95]
	v_mfma_f32_16x16x32_bf16 v[88:91], v[156:159], v[194:197], v[88:91]
	v_mfma_f32_16x16x32_bf16 v[76:79], v[148:151], v[202:205], v[76:79]
	v_mfma_f32_16x16x32_bf16 v[72:75], v[156:159], v[202:205], v[72:75]
	v_mfma_f32_16x16x32_bf16 v[60:63], v[148:151], v[218:221], v[60:63]
	v_mfma_f32_16x16x32_bf16 v[56:59], v[156:159], v[218:221], v[56:59]
	v_mfma_f32_16x16x32_bf16 v[44:47], v[148:151], v[226:229], v[44:47]
	v_mfma_f32_16x16x32_bf16 v[40:43], v[156:159], v[226:229], v[40:43]
	v_mfma_f32_16x16x32_bf16 v[28:31], v[148:151], v[234:237], v[28:31]
	v_mfma_f32_16x16x32_bf16 v[24:27], v[156:159], v[234:237], v[24:27]
	s_waitcnt lgkmcnt(0)
	v_mfma_f32_16x16x32_bf16 v[12:15], v[148:151], v[242:245], v[12:15]
	v_mfma_f32_16x16x32_bf16 v[8:11], v[156:159], v[242:245], v[8:11]
	s_barrier
	s_add_u32 s4, s80, 0x80
	ds_read_b128 v[130:133], v146
	ds_read_b128 v[148:151], v146 offset:1024
	ds_read_b128 v[152:155], v146 offset:2048
	ds_read_b128 v[156:159], v146 offset:3072
	s_addc_u32 s5, s81, 0
	s_mov_b32 m0, s52
	s_nop 0
	global_load_lds_dwordx4 v137, s[4:5]
	s_mov_b32 m0, s53
	s_nop 0
	global_load_lds_dwordx4 v139, s[4:5]
	s_mov_b32 m0, s54
	s_nop 0
	global_load_lds_dwordx4 v136, s[38:39]
	s_mov_b32 m0, s55
	s_nop 0
	global_load_lds_dwordx4 v138, s[38:39]
	s_add_u32 s4, s10, 0x40080
	s_addc_u32 s5, s11, 0
	s_mov_b32 m0, s82
	s_nop 0
	global_load_lds_dwordx4 v136, s[4:5]
	s_mov_b32 m0, s83
	s_nop 0
	global_load_lds_dwordx4 v138, s[4:5]
	s_waitcnt vmcnt(8)
	s_cmp_lg_u64 s[2:3], 0
	s_cbranch_scc1 .Lh0skip_3
	s_waitcnt lgkmcnt(0)
.Lh0skip_3:
	s_barrier
	s_waitcnt lgkmcnt(3)
	v_mfma_f32_16x16x32_bf16 v[116:119], v[130:133], v[166:169], v[116:119]
	s_waitcnt lgkmcnt(1)
	v_mfma_f32_16x16x32_bf16 v[112:115], v[152:155], v[166:169], v[112:115]
	v_mfma_f32_16x16x32_bf16 v[100:103], v[130:133], v[182:185], v[100:103]
	v_mfma_f32_16x16x32_bf16 v[96:99], v[152:155], v[182:185], v[96:99]
	v_mfma_f32_16x16x32_bf16 v[84:87], v[130:133], v[190:193], v[84:87]
	v_mfma_f32_16x16x32_bf16 v[80:83], v[152:155], v[190:193], v[80:83]
	v_mfma_f32_16x16x32_bf16 v[68:71], v[130:133], v[198:201], v[68:71]
	v_mfma_f32_16x16x32_bf16 v[64:67], v[152:155], v[198:201], v[64:67]
	v_mfma_f32_16x16x32_bf16 v[52:55], v[130:133], v[214:217], v[52:55]
	v_mfma_f32_16x16x32_bf16 v[48:51], v[152:155], v[214:217], v[48:51]
	v_mfma_f32_16x16x32_bf16 v[36:39], v[130:133], v[222:225], v[36:39]
	v_mfma_f32_16x16x32_bf16 v[32:35], v[152:155], v[222:225], v[32:35]
	v_mfma_f32_16x16x32_bf16 v[20:23], v[130:133], v[230:233], v[20:23]
	v_mfma_f32_16x16x32_bf16 v[16:19], v[152:155], v[230:233], v[16:19]
	v_mfma_f32_16x16x32_bf16 v[4:7], v[130:133], v[238:241], v[4:7]
	v_mfma_f32_16x16x32_bf16 v[0:3], v[152:155], v[238:241], v[0:3]
	v_mfma_f32_16x16x32_bf16 v[116:119], v[148:151], v[178:181], v[116:119]
	s_waitcnt lgkmcnt(0)
	v_mfma_f32_16x16x32_bf16 v[112:115], v[156:159], v[178:181], v[112:115]
	v_mfma_f32_16x16x32_bf16 v[100:103], v[148:151], v[186:189], v[100:103]
	v_mfma_f32_16x16x32_bf16 v[96:99], v[156:159], v[186:189], v[96:99]
	v_mfma_f32_16x16x32_bf16 v[84:87], v[148:151], v[194:197], v[84:87]
	v_mfma_f32_16x16x32_bf16 v[80:83], v[156:159], v[194:197], v[80:83]
	v_mfma_f32_16x16x32_bf16 v[68:71], v[148:151], v[202:205], v[68:71]
	v_mfma_f32_16x16x32_bf16 v[64:67], v[156:159], v[202:205], v[64:67]
	v_mfma_f32_16x16x32_bf16 v[52:55], v[148:151], v[218:221], v[52:55]
	v_mfma_f32_16x16x32_bf16 v[48:51], v[156:159], v[218:221], v[48:51]
	v_mfma_f32_16x16x32_bf16 v[36:39], v[148:151], v[226:229], v[36:39]
	v_mfma_f32_16x16x32_bf16 v[32:35], v[156:159], v[226:229], v[32:35]
	v_mfma_f32_16x16x32_bf16 v[20:23], v[148:151], v[234:237], v[20:23]
	v_mfma_f32_16x16x32_bf16 v[16:19], v[156:159], v[234:237], v[16:19]
	v_mfma_f32_16x16x32_bf16 v[4:7], v[148:151], v[242:245], v[4:7]
	v_mfma_f32_16x16x32_bf16 v[0:3], v[156:159], v[242:245], v[0:3]
	s_barrier
	s_add_i32 s62, s62, 2
	s_add_u32 s60, s60, 0x100
	s_addc_u32 s61, s61, 0
	s_cmp_gt_u32 s62, 13
	s_mov_b64 s[4:5], s[8:9]
	s_cbranch_scc0 .LBB0_233
	s_and_b64 vcc, exec, s[2:3]
	s_cbranch_vccz .LBB0_236
	s_barrier

; #define PG8_STAGE(bufoff, gbase, voff) do { _Pragma("unroll") for (int _i = 0; _i < 2; ++_i) { \
;         const unsigned _m0 = ldsu + (unsigned)(bufoff) + ldsw + (unsigned)(_i * 8192); \
;         asm volatile("s_mov_b32 m0, %2\n\ts_nop 0\n\tglobal_load_lds_dwordx4 %0, %1" :: "v"((voff)[_i]), "s"((const char*)(gbase)), "s"(_m0) : "memory"); } } while (0)
; #define PG8_LDA(dst, b, h) do { _Pragma("unroll") for (int m = 0; m < 4; ++m) _Pragma("unroll") for (int k = 0; k < 2; ++k) dst[m][k] = *(const LAS bf16x8*)(lds + PG8_SA(b, h) + aoff + m * 2048 + k * 1024); } while (0)
; #define PG8_LDB(dst, b, h) do { _Pragma("unroll") for (int n = 0; n < 2; ++n) _Pragma("unroll") for (int k = 0; k < 2; ++k) dst[n][k] = *(const LAS bf16x8*)(lds + bbase[b][h] + n * 2048 + k * 1024); } while (0)
; #define PG8_WAIT_V(n) asm volatile("s_waitcnt vmcnt(" #n ")" ::: "memory")
; #define PG8_WAIT_L(n) asm volatile("s_waitcnt lgkmcnt(" #n ")" ::: "memory")
; #define PG8_BAR __builtin_amdgcn_s_barrier()
; #define PG8_SCHED __builtin_amdgcn_sched_barrier(0)
; template <class Epi>
; __device__ __forceinline__ void gemm_phase(LAS unsigned char* lds, const Gemm g, const StaticOrder& S, const Epi& E) {
;     ...
;             PG8_LDB(B0, 0, 0); PG8_SCHED; PG8_LDA(At, 0, 0); PG8_LDA(At2, 0, 1); PG8_STAGE(PG8_SB(1, 1), b1 + hstepB, voffB);
;             PG8_WAIT_V(8); PG8_WAIT_L(0); PG8_BAR; PG8_MMA2B(0, At, At2, B0); PG8_BAR; PG8_SCHED;
;             PG8_LDB(B0, 0, 1); PG8_STAGE(PG8_SB(0, 0), b2, voffB); PG8_STAGE(PG8_SA(0, 0), a2, voffA); PG8_STAGE(PG8_SA(0, 1), a2 + hstepA, voffA);
;             PG8_WAIT_V(8); PG8_WAIT_L(0); PG8_BAR; PG8_MMA2B(1, At, At2, B0); PG8_BAR; PG8_SCHED;
.LBB0_584:
	ds_read_b128 v[128:131], v155
	ds_read_b128 v[132:135], v155 offset:1024
	ds_read_b128 v[136:139], v155 offset:2048
	ds_read_b128 v[140:143], v155 offset:3072
	s_add_u32 s10, s8, 0x100
	s_addc_u32 s11, s9, 0
	s_cmp_eq_u32 s68, 12
	s_cselect_b32 s84, s67, s87
	s_cselect_b32 s85, s43, s88
	s_cselect_b32 s90, s86, s10
	s_cselect_b32 s91, s39, s11
	s_add_u32 s96, s84, 0x80
	s_addc_u32 s97, s85, 0
	ds_read_b128 v[144:147], v156
	ds_read_b128 v[178:181], v156 offset:1024
	ds_read_b128 v[182:185], v156 offset:2048
	ds_read_b128 v[186:189], v156 offset:3072
	ds_read_b128 v[190:193], v156 offset:4096
	ds_read_b128 v[194:197], v156 offset:5120
	ds_read_b128 v[198:201], v156 offset:6144
	ds_read_b128 v[202:205], v156 offset:7168
	ds_read_b128 v[214:217], v156 offset:16384
	ds_read_b128 v[218:221], v156 offset:17408
	ds_read_b128 v[222:225], v156 offset:18432
	ds_read_b128 v[226:229], v156 offset:19456
	ds_read_b128 v[230:233], v156 offset:20480
	ds_read_b128 v[234:237], v156 offset:21504
	ds_read_b128 v[238:241], v156 offset:22528
	ds_read_b128 v[242:245], v156 offset:23552
	s_add_u32 s8, s8, 0x40080
	s_addc_u32 s9, s9, 0
	s_mov_b32 m0, s61
	s_nop 0
	global_load_lds_dwordx4 v151, s[8:9]
	s_mov_b32 m0, s64
	s_nop 0
	global_load_lds_dwordx4 v153, s[8:9]
	s_waitcnt vmcnt(8)
	s_cmp_lg_u64 s[4:5], 0
	s_cbranch_scc1 .Lh0skip_4
	s_waitcnt lgkmcnt(0)
.Lh0skip_4:
	s_barrier
	s_waitcnt lgkmcnt(14)
	v_mfma_f32_16x16x32_bf16 v[76:79], v[128:131], v[144:147], v[76:79]
	v_mfma_f32_16x16x32_bf16 v[72:75], v[136:139], v[144:147], v[72:75]
	s_waitcnt lgkmcnt(13)
	v_mfma_f32_16x16x32_bf16 v[64:67], v[128:131], v[182:185], v[64:67]
	v_mfma_f32_16x16x32_bf16 v[60:63], v[136:139], v[182:185], v[60:63]
	s_waitcnt lgkmcnt(11)
	v_mfma_f32_16x16x32_bf16 v[56:59], v[128:131], v[190:193], v[56:59]
	v_mfma_f32_16x16x32_bf16 v[52:55], v[136:139], v[190:193], v[52:55]
	s_waitcnt lgkmcnt(9)
	v_mfma_f32_16x16x32_bf16 v[112:115], v[128:131], v[198:201], v[112:115]
	v_mfma_f32_16x16x32_bf16 v[104:107], v[136:139], v[198:201], v[104:107]
	s_waitcnt lgkmcnt(7)
	v_mfma_f32_16x16x32_bf16 v[36:39], v[128:131], v[214:217], v[36:39]
	v_mfma_f32_16x16x32_bf16 v[32:35], v[136:139], v[214:217], v[32:35]
	s_waitcnt lgkmcnt(5)
	v_mfma_f32_16x16x32_bf16 v[28:31], v[128:131], v[222:225], v[28:31]
	v_mfma_f32_16x16x32_bf16 v[24:27], v[136:139], v[222:225], v[24:27]
	s_waitcnt lgkmcnt(3)
	v_mfma_f32_16x16x32_bf16 v[16:19], v[128:131], v[230:233], v[16:19]
	v_mfma_f32_16x16x32_bf16 v[12:15], v[136:139], v[230:233], v[12:15]
	s_waitcnt lgkmcnt(1)
	v_mfma_f32_16x16x32_bf16 v[88:91], v[128:131], v[238:241], v[88:91]
	v_mfma_f32_16x16x32_bf16 v[84:87], v[136:139], v[238:241], v[84:87]
	v_mfma_f32_16x16x32_bf16 v[76:79], v[132:135], v[178:181], v[76:79]
	v_mfma_f32_16x16x32_bf16 v[72:75], v[140:143], v[178:181], v[72:75]
	v_mfma_f32_16x16x32_bf16 v[64:67], v[132:135], v[186:189], v[64:67]
	v_mfma_f32_16x16x32_bf16 v[60:63], v[140:143], v[186:189], v[60:63]
	v_mfma_f32_16x16x32_bf16 v[56:59], v[132:135], v[194:197], v[56:59]
	v_mfma_f32_16x16x32_bf16 v[52:55], v[140:143], v[194:197], v[52:55]
	v_mfma_f32_16x16x32_bf16 v[112:115], v[132:135], v[202:205], v[112:115]
	v_mfma_f32_16x16x32_bf16 v[104:107], v[140:143], v[202:205], v[104:107]
	v_mfma_f32_16x16x32_bf16 v[36:39], v[132:135], v[218:221], v[36:39]
	v_mfma_f32_16x16x32_bf16 v[32:35], v[140:143], v[218:221], v[32:35]
	v_mfma_f32_16x16x32_bf16 v[28:31], v[132:135], v[226:229], v[28:31]
	v_mfma_f32_16x16x32_bf16 v[24:27], v[140:143], v[226:229], v[24:27]
	v_mfma_f32_16x16x32_bf16 v[16:19], v[132:135], v[234:237], v[16:19]
	v_mfma_f32_16x16x32_bf16 v[12:15], v[140:143], v[234:237], v[12:15]
	s_waitcnt lgkmcnt(0)
	v_mfma_f32_16x16x32_bf16 v[88:91], v[132:135], v[242:245], v[88:91]
	v_mfma_f32_16x16x32_bf16 v[84:87], v[140:143], v[242:245], v[84:87]
	s_barrier
	ds_read_b128 v[128:131], v157
	ds_read_b128 v[132:135], v157 offset:1024
	ds_read_b128 v[136:139], v157 offset:2048
	ds_read_b128 v[140:143], v157 offset:3072
	s_mov_b32 m0, s47
	s_nop 0
	global_load_lds_dwordx4 v151, s[90:91]
	s_mov_b32 m0, s48
	s_nop 0
	global_load_lds_dwordx4 v153, s[90:91]
	s_mov_b32 m0, s37
	s_nop 0
	global_load_lds_dwordx4 v150, s[84:85]
	s_mov_b32 m0, s49
	s_nop 0
	global_load_lds_dwordx4 v152, s[84:85]
	s_add_u32 s8, s84, 0x40000
	s_addc_u32 s9, s85, 0
	s_mov_b32 m0, s50
	s_nop 0
	global_load_lds_dwordx4 v150, s[8:9]
	s_mov_b32 m0, s51
	s_nop 0
	global_load_lds_dwordx4 v152, s[8:9]
	s_waitcnt vmcnt(8)
	s_cmp_lg_u64 s[4:5], 0
	s_cbranch_scc1 .Lh0skip_5
	s_waitcnt lgkmcnt(0)
; #define PG8_STAGE(bufoff, gbase, voff) do { _Pragma("unroll") for (int _i = 0; _i < 2; ++_i) { \
;         const unsigned _m0 = ldsu + (unsigned)(bufoff) + ldsw + (unsigned)(_i * 8192); \
;         asm volatile("s_mov_b32 m0, %2\n\ts_nop 0\n\tglobal_load_lds_dwordx4 %0, %1" :: "v"((voff)[_i]), "s"((const char*)(gbase)), "s"(_m0) : "memory"); } } while (0)
; #define PG8_LDA(dst, b, h) do { _Pragma("unroll") for (int m = 0; m < 4; ++m) _Pragma("unroll") for (int k = 0; k < 2; ++k) dst[m][k] = *(const LAS bf16x8*)(lds + PG8_SA(b, h) + aoff + m * 2048 + k * 1024); } while (0)
; #define PG8_LDB(dst, b, h) do { _Pragma("unroll") for (int n = 0; n < 2; ++n) _Pragma("unroll") for (int k = 0; k < 2; ++k) dst[n][k] = *(const LAS bf16x8*)(lds + bbase[b][h] + n * 2048 + k * 1024); } while (0)
; #define PG8_WAIT_V(n) asm volatile("s_waitcnt vmcnt(" #n ")" ::: "memory")
; #define PG8_WAIT_L(n) asm volatile("s_waitcnt lgkmcnt(" #n ")" ::: "memory")
; #define PG8_BAR __builtin_amdgcn_s_barrier()
; #define PG8_SCHED __builtin_amdgcn_sched_barrier(0)
; template <class Epi>
; __device__ __forceinline__ void gemm_phase(LAS unsigned char* lds, const Gemm g, const StaticOrder& S, const Epi& E) {
;     ...
;             PG8_WAIT_V(8); PG8_WAIT_L(0); PG8_BAR; PG8_MMA2B(1, At, At2, B0); PG8_BAR; PG8_SCHED;
;             PG8_LDB(B0, 1, 0); PG8_SCHED; PG8_LDA(At, 1, 0); PG8_LDA(At2, 1, 1); PG8_STAGE(PG8_SB(0, 1), b2 + hstepB, voffB);
;             PG8_WAIT_V(8); PG8_WAIT_L(0); PG8_BAR; PG8_MMA2B(0, At, At2, B0); PG8_BAR; PG8_SCHED;
.Lh0skip_5:
	s_barrier
	s_waitcnt lgkmcnt(3)
	v_mfma_f32_16x16x32_bf16 v[68:71], v[128:131], v[144:147], v[68:71]
	s_waitcnt lgkmcnt(1)
	v_mfma_f32_16x16x32_bf16 v[124:127], v[136:139], v[144:147], v[124:127]
	v_mfma_f32_16x16x32_bf16 v[48:51], v[128:131], v[182:185], v[48:51]
	v_mfma_f32_16x16x32_bf16 v[120:123], v[136:139], v[182:185], v[120:123]
	v_mfma_f32_16x16x32_bf16 v[44:47], v[128:131], v[190:193], v[44:47]
	v_mfma_f32_16x16x32_bf16 v[116:119], v[136:139], v[190:193], v[116:119]
	v_mfma_f32_16x16x32_bf16 v[40:43], v[128:131], v[198:201], v[40:43]
	v_mfma_f32_16x16x32_bf16 v[108:111], v[136:139], v[198:201], v[108:111]
	v_mfma_f32_16x16x32_bf16 v[20:23], v[128:131], v[214:217], v[20:23]
	v_mfma_f32_16x16x32_bf16 v[100:103], v[136:139], v[214:217], v[100:103]
	v_mfma_f32_16x16x32_bf16 v[8:11], v[128:131], v[222:225], v[8:11]
	v_mfma_f32_16x16x32_bf16 v[96:99], v[136:139], v[222:225], v[96:99]
	v_mfma_f32_16x16x32_bf16 v[4:7], v[128:131], v[230:233], v[4:7]
	v_mfma_f32_16x16x32_bf16 v[92:95], v[136:139], v[230:233], v[92:95]
	v_mfma_f32_16x16x32_bf16 v[0:3], v[128:131], v[238:241], v[0:3]
	v_mfma_f32_16x16x32_bf16 v[80:83], v[136:139], v[238:241], v[80:83]
	v_mfma_f32_16x16x32_bf16 v[68:71], v[132:135], v[178:181], v[68:71]
	s_waitcnt lgkmcnt(0)
	v_mfma_f32_16x16x32_bf16 v[124:127], v[140:143], v[178:181], v[124:127]
	v_mfma_f32_16x16x32_bf16 v[48:51], v[132:135], v[186:189], v[48:51]
	v_mfma_f32_16x16x32_bf16 v[120:123], v[140:143], v[186:189], v[120:123]
	v_mfma_f32_16x16x32_bf16 v[44:47], v[132:135], v[194:197], v[44:47]
	v_mfma_f32_16x16x32_bf16 v[116:119], v[140:143], v[194:197], v[116:119]
	v_mfma_f32_16x16x32_bf16 v[40:43], v[132:135], v[202:205], v[40:43]
	v_mfma_f32_16x16x32_bf16 v[108:111], v[140:143], v[202:205], v[108:111]
	v_mfma_f32_16x16x32_bf16 v[20:23], v[132:135], v[218:221], v[20:23]
	v_mfma_f32_16x16x32_bf16 v[100:103], v[140:143], v[218:221], v[100:103]
	v_mfma_f32_16x16x32_bf16 v[8:11], v[132:135], v[226:229], v[8:11]
	v_mfma_f32_16x16x32_bf16 v[96:99], v[140:143], v[226:229], v[96:99]
	v_mfma_f32_16x16x32_bf16 v[4:7], v[132:135], v[234:237], v[4:7]
	v_mfma_f32_16x16x32_bf16 v[92:95], v[140:143], v[234:237], v[92:95]
	v_mfma_f32_16x16x32_bf16 v[0:3], v[132:135], v[242:245], v[0:3]
	v_mfma_f32_16x16x32_bf16 v[80:83], v[140:143], v[242:245], v[80:83]
	s_barrier
	ds_read_b128 v[128:131], v158
	ds_read_b128 v[132:135], v158 offset:1024
	ds_read_b128 v[136:139], v158 offset:2048
	ds_read_b128 v[140:143], v158 offset:3072
	ds_read_b128 v[144:147], v156 offset:32768
	ds_read_b128 v[178:181], v156 offset:33792
	ds_read_b128 v[182:185], v156 offset:34816
	ds_read_b128 v[186:189], v156 offset:35840
	ds_read_b128 v[190:193], v156 offset:36864
	ds_read_b128 v[194:197], v156 offset:37888
	ds_read_b128 v[198:201], v156 offset:38912
	ds_read_b128 v[202:205], v156 offset:39936
	ds_read_b128 v[214:217], v156 offset:49152
	ds_read_b128 v[218:221], v156 offset:50176
	ds_read_b128 v[222:225], v156 offset:51200
	ds_read_b128 v[226:229], v156 offset:52224
	ds_read_b128 v[230:233], v156 offset:53248
	ds_read_b128 v[234:237], v156 offset:54272
	ds_read_b128 v[238:241], v156 offset:55296
	ds_read_b128 v[242:245], v156 offset:56320
	s_add_u32 s8, s90, 0x40000
	s_addc_u32 s9, s91, 0
	s_mov_b32 m0, s52
	s_nop 0
	global_load_lds_dwordx4 v151, s[8:9]
	s_mov_b32 m0, s53
	s_nop 0
	global_load_lds_dwordx4 v153, s[8:9]
	s_waitcnt vmcnt(8)
	s_cmp_lg_u64 s[4:5], 0
	s_cbranch_scc1 .Lh0skip_6
	s_waitcnt lgkmcnt(0)
; #define PG8_STAGE(bufoff, gbase, voff) do { _Pragma("unroll") for (int _i = 0; _i < 2; ++_i) { \
;         const unsigned _m0 = ldsu + (unsigned)(bufoff) + ldsw + (unsigned)(_i * 8192); \
;         asm volatile("s_mov_b32 m0, %2\n\ts_nop 0\n\tglobal_load_lds_dwordx4 %0, %1" :: "v"((voff)[_i]), "s"((const char*)(gbase)), "s"(_m0) : "memory"); } } while (0)
; #define PG8_LDB(dst, b, h) do { _Pragma("unroll") for (int n = 0; n < 2; ++n) _Pragma("unroll") for (int k = 0; k < 2; ++k) dst[n][k] = *(const LAS bf16x8*)(lds + bbase[b][h] + n * 2048 + k * 1024); } while (0)
; #define PG8_WAIT_V(n) asm volatile("s_waitcnt vmcnt(" #n ")" ::: "memory")
; #define PG8_WAIT_L(n) asm volatile("s_waitcnt lgkmcnt(" #n ")" ::: "memory")
; #define PG8_BAR __builtin_amdgcn_s_barrier()
; #define PG8_SCHED __builtin_amdgcn_sched_barrier(0)
; template <class Epi>
; __device__ __forceinline__ void gemm_phase(LAS unsigned char* lds, const Gemm g, const StaticOrder& S, const Epi& E) {
;     ...
;             PG8_WAIT_V(8); PG8_WAIT_L(0); PG8_BAR; PG8_MMA2B(0, At, At2, B0); PG8_BAR; PG8_SCHED;
;             PG8_LDB(B0, 1, 1); PG8_STAGE(PG8_SB(1, 0), b3, voffB); PG8_STAGE(PG8_SA(1, 0), a3, voffA); PG8_STAGE(PG8_SA(1, 1), a3 + hstepA, voffA);
;             PG8_WAIT_V(8); PG8_WAIT_L(0); PG8_BAR; PG8_MMA2B(1, At, At2, B0); PG8_BAR; PG8_SCHED;
;         }
;         if (wr == 0) PG8_BAR;
.Lh0skip_6:
	s_barrier
	s_waitcnt lgkmcnt(14)
	v_mfma_f32_16x16x32_bf16 v[76:79], v[128:131], v[144:147], v[76:79]
	v_mfma_f32_16x16x32_bf16 v[72:75], v[136:139], v[144:147], v[72:75]
	s_waitcnt lgkmcnt(13)
	v_mfma_f32_16x16x32_bf16 v[64:67], v[128:131], v[182:185], v[64:67]
	v_mfma_f32_16x16x32_bf16 v[60:63], v[136:139], v[182:185], v[60:63]
	s_waitcnt lgkmcnt(11)
	v_mfma_f32_16x16x32_bf16 v[56:59], v[128:131], v[190:193], v[56:59]
	v_mfma_f32_16x16x32_bf16 v[52:55], v[136:139], v[190:193], v[52:55]
	s_waitcnt lgkmcnt(9)
	v_mfma_f32_16x16x32_bf16 v[112:115], v[128:131], v[198:201], v[112:115]
	v_mfma_f32_16x16x32_bf16 v[104:107], v[136:139], v[198:201], v[104:107]
	s_waitcnt lgkmcnt(7)
	v_mfma_f32_16x16x32_bf16 v[36:39], v[128:131], v[214:217], v[36:39]
	v_mfma_f32_16x16x32_bf16 v[32:35], v[136:139], v[214:217], v[32:35]
	s_waitcnt lgkmcnt(5)
	v_mfma_f32_16x16x32_bf16 v[28:31], v[128:131], v[222:225], v[28:31]
	v_mfma_f32_16x16x32_bf16 v[24:27], v[136:139], v[222:225], v[24:27]
	s_waitcnt lgkmcnt(3)
	v_mfma_f32_16x16x32_bf16 v[16:19], v[128:131], v[230:233], v[16:19]
	v_mfma_f32_16x16x32_bf16 v[12:15], v[136:139], v[230:233], v[12:15]
	s_waitcnt lgkmcnt(1)
	v_mfma_f32_16x16x32_bf16 v[88:91], v[128:131], v[238:241], v[88:91]
	v_mfma_f32_16x16x32_bf16 v[84:87], v[136:139], v[238:241], v[84:87]
	v_mfma_f32_16x16x32_bf16 v[76:79], v[132:135], v[178:181], v[76:79]
	v_mfma_f32_16x16x32_bf16 v[72:75], v[140:143], v[178:181], v[72:75]
	v_mfma_f32_16x16x32_bf16 v[64:67], v[132:135], v[186:189], v[64:67]
	v_mfma_f32_16x16x32_bf16 v[60:63], v[140:143], v[186:189], v[60:63]
	v_mfma_f32_16x16x32_bf16 v[56:59], v[132:135], v[194:197], v[56:59]
	v_mfma_f32_16x16x32_bf16 v[52:55], v[140:143], v[194:197], v[52:55]
	v_mfma_f32_16x16x32_bf16 v[112:115], v[132:135], v[202:205], v[112:115]
	v_mfma_f32_16x16x32_bf16 v[104:107], v[140:143], v[202:205], v[104:107]
	v_mfma_f32_16x16x32_bf16 v[36:39], v[132:135], v[218:221], v[36:39]
	v_mfma_f32_16x16x32_bf16 v[32:35], v[140:143], v[218:221], v[32:35]
	v_mfma_f32_16x16x32_bf16 v[28:31], v[132:135], v[226:229], v[28:31]
	v_mfma_f32_16x16x32_bf16 v[24:27], v[140:143], v[226:229], v[24:27]
	v_mfma_f32_16x16x32_bf16 v[16:19], v[132:135], v[234:237], v[16:19]
	v_mfma_f32_16x16x32_bf16 v[12:15], v[140:143], v[234:237], v[12:15]
	s_waitcnt lgkmcnt(0)
	v_mfma_f32_16x16x32_bf16 v[88:91], v[132:135], v[242:245], v[88:91]
	v_mfma_f32_16x16x32_bf16 v[84:87], v[140:143], v[242:245], v[84:87]
	s_barrier
	s_add_u32 s8, s90, 0x80
	ds_read_b128 v[128:131], v159
	ds_read_b128 v[132:135], v159 offset:1024
	ds_read_b128 v[136:139], v159 offset:2048
	ds_read_b128 v[140:143], v159 offset:3072
	s_addc_u32 s9, s91, 0
	s_mov_b32 m0, s55
	s_nop 0
	global_load_lds_dwordx4 v151, s[8:9]
	s_mov_b32 m0, s56
	s_nop 0
	global_load_lds_dwordx4 v153, s[8:9]
	s_mov_b32 m0, s57
	s_nop 0
	global_load_lds_dwordx4 v150, s[96:97]
	s_mov_b32 m0, s58
	s_nop 0
	global_load_lds_dwordx4 v152, s[96:97]
	s_add_u32 s8, s84, 0x40080
	s_addc_u32 s9, s85, 0
	s_mov_b32 m0, s59
	s_nop 0
	global_load_lds_dwordx4 v150, s[8:9]
	s_mov_b32 m0, s60
	s_nop 0
	global_load_lds_dwordx4 v152, s[8:9]
	s_waitcnt vmcnt(8)
	s_cmp_lg_u64 s[4:5], 0
	s_cbranch_scc1 .Lh0skip_7
	s_waitcnt lgkmcnt(0)
.Lh0skip_7:
	s_barrier
	s_waitcnt lgkmcnt(3)
	v_mfma_f32_16x16x32_bf16 v[68:71], v[128:131], v[144:147], v[68:71]
	s_waitcnt lgkmcnt(1)
	v_mfma_f32_16x16x32_bf16 v[124:127], v[136:139], v[144:147], v[124:127]
	v_mfma_f32_16x16x32_bf16 v[48:51], v[128:131], v[182:185], v[48:51]
	v_mfma_f32_16x16x32_bf16 v[120:123], v[136:139], v[182:185], v[120:123]
	v_mfma_f32_16x16x32_bf16 v[44:47], v[128:131], v[190:193], v[44:47]
	v_mfma_f32_16x16x32_bf16 v[116:119], v[136:139], v[190:193], v[116:119]
	v_mfma_f32_16x16x32_bf16 v[40:43], v[128:131], v[198:201], v[40:43]
	v_mfma_f32_16x16x32_bf16 v[108:111], v[136:139], v[198:201], v[108:111]
	v_mfma_f32_16x16x32_bf16 v[20:23], v[128:131], v[214:217], v[20:23]
	v_mfma_f32_16x16x32_bf16 v[100:103], v[136:139], v[214:217], v[100:103]
	v_mfma_f32_16x16x32_bf16 v[8:11], v[128:131], v[222:225], v[8:11]
	v_mfma_f32_16x16x32_bf16 v[96:99], v[136:139], v[222:225], v[96:99]
	v_mfma_f32_16x16x32_bf16 v[4:7], v[128:131], v[230:233], v[4:7]
	v_mfma_f32_16x16x32_bf16 v[92:95], v[136:139], v[230:233], v[92:95]
	v_mfma_f32_16x16x32_bf16 v[0:3], v[128:131], v[238:241], v[0:3]
	v_mfma_f32_16x16x32_bf16 v[80:83], v[136:139], v[238:241], v[80:83]
	v_mfma_f32_16x16x32_bf16 v[68:71], v[132:135], v[178:181], v[68:71]
	s_waitcnt lgkmcnt(0)
	v_mfma_f32_16x16x32_bf16 v[124:127], v[140:143], v[178:181], v[124:127]
	v_mfma_f32_16x16x32_bf16 v[48:51], v[132:135], v[186:189], v[48:51]
	v_mfma_f32_16x16x32_bf16 v[120:123], v[140:143], v[186:189], v[120:123]
	v_mfma_f32_16x16x32_bf16 v[44:47], v[132:135], v[194:197], v[44:47]
	v_mfma_f32_16x16x32_bf16 v[116:119], v[140:143], v[194:197], v[116:119]
	v_mfma_f32_16x16x32_bf16 v[40:43], v[132:135], v[202:205], v[40:43]
	v_mfma_f32_16x16x32_bf16 v[108:111], v[140:143], v[202:205], v[108:111]
	v_mfma_f32_16x16x32_bf16 v[20:23], v[132:135], v[218:221], v[20:23]
	v_mfma_f32_16x16x32_bf16 v[100:103], v[140:143], v[218:221], v[100:103]
	v_mfma_f32_16x16x32_bf16 v[8:11], v[132:135], v[226:229], v[8:11]
	v_mfma_f32_16x16x32_bf16 v[96:99], v[140:143], v[226:229], v[96:99]
	v_mfma_f32_16x16x32_bf16 v[4:7], v[132:135], v[234:237], v[4:7]
	v_mfma_f32_16x16x32_bf16 v[92:95], v[140:143], v[234:237], v[92:95]
	v_mfma_f32_16x16x32_bf16 v[0:3], v[132:135], v[242:245], v[0:3]
	v_mfma_f32_16x16x32_bf16 v[80:83], v[140:143], v[242:245], v[80:83]
	s_barrier
	s_add_i32 s68, s68, 2
	s_add_u32 s87, s87, 0x100
	s_addc_u32 s88, s88, 0
	s_cmp_gt_u32 s68, 13
	s_mov_b64 s[8:9], s[10:11]
	s_cbranch_scc0 .LBB0_584
	s_and_b64 vcc, exec, s[4:5]
	s_cbranch_vccz .LBB0_587
	s_barrier

; #define PG8_STAGE(bufoff, gbase, voff) do { _Pragma("unroll") for (int _i = 0; _i < 2; ++_i) { \
;         const unsigned _m0 = ldsu + (unsigned)(bufoff) + ldsw + (unsigned)(_i * 8192); \
;         asm volatile("s_mov_b32 m0, %2\n\ts_nop 0\n\tglobal_load_lds_dwordx4 %0, %1" :: "v"((voff)[_i]), "s"((const char*)(gbase)), "s"(_m0) : "memory"); } } while (0)
; #define PG8_LDA(dst, b, h) do { _Pragma("unroll") for (int m = 0; m < 4; ++m) _Pragma("unroll") for (int k = 0; k < 2; ++k) dst[m][k] = *(const LAS bf16x8*)(lds + PG8_SA(b, h) + aoff + m * 2048 + k * 1024); } while (0)
; #define PG8_LDB(dst, b, h) do { _Pragma("unroll") for (int n = 0; n < 2; ++n) _Pragma("unroll") for (int k = 0; k < 2; ++k) dst[n][k] = *(const LAS bf16x8*)(lds + bbase[b][h] + n * 2048 + k * 1024); } while (0)
; #define PG8_WAIT_V(n) asm volatile("s_waitcnt vmcnt(" #n ")" ::: "memory")
; #define PG8_WAIT_L(n) asm volatile("s_waitcnt lgkmcnt(" #n ")" ::: "memory")
; #define PG8_BAR __builtin_amdgcn_s_barrier()
; #define PG8_SCHED __builtin_amdgcn_sched_barrier(0)
; template <class Epi>
; __device__ __forceinline__ void gemm_phase(LAS unsigned char* lds, const Gemm g, const StaticOrder& S, const Epi& E) {
;     ...
;             PG8_LDB(B0, 0, 0); PG8_SCHED; PG8_LDA(At, 0, 0); PG8_LDA(At2, 0, 1); PG8_STAGE(PG8_SB(1, 1), b1 + hstepB, voffB);
;             PG8_WAIT_V(8); PG8_WAIT_L(0); PG8_BAR; PG8_MMA2B(0, At, At2, B0); PG8_BAR; PG8_SCHED;
;             PG8_LDB(B0, 0, 1); PG8_STAGE(PG8_SB(0, 0), b2, voffB); PG8_STAGE(PG8_SA(0, 0), a2, voffA); PG8_STAGE(PG8_SA(0, 1), a2 + hstepA, voffA);
;             PG8_WAIT_V(8); PG8_WAIT_L(0); PG8_BAR; PG8_MMA2B(1, At, At2, B0); PG8_BAR; PG8_SCHED;
.LBB0_943:
	ds_read_b128 v[128:131], v138
	ds_read_b128 v[144:147], v138 offset:1024
	ds_read_b128 v[148:151], v138 offset:2048
	ds_read_b128 v[152:155], v138 offset:3072
	s_cmp_eq_u32 s68, 12
	s_cselect_b32 s38, s66, s84
	s_cselect_b32 s39, s13, s85
	s_cselect_b32 s82, s67, s86
	s_cselect_b32 s83, s5, s87
	s_add_u32 s42, s38, 0x80
	s_addc_u32 s43, s39, 0
	s_add_u32 s80, s82, 0x80
	s_addc_u32 s81, s83, 0
	ds_read_b128 v[156:159], v139
	ds_read_b128 v[166:169], v139 offset:1024
	ds_read_b128 v[178:181], v139 offset:2048
	ds_read_b128 v[182:185], v139 offset:3072
	ds_read_b128 v[186:189], v139 offset:4096
	ds_read_b128 v[190:193], v139 offset:5120
	ds_read_b128 v[194:197], v139 offset:6144
	ds_read_b128 v[198:201], v139 offset:7168
	ds_read_b128 v[202:205], v139 offset:16384
	ds_read_b128 v[214:217], v139 offset:17408
	ds_read_b128 v[218:221], v139 offset:18432
	ds_read_b128 v[222:225], v139 offset:19456
	ds_read_b128 v[226:229], v139 offset:20480
	ds_read_b128 v[230:233], v139 offset:21504
	ds_read_b128 v[234:237], v139 offset:22528
	ds_read_b128 v[238:241], v139 offset:23552
	s_mov_b32 m0, s61
	s_nop 0
	global_load_lds_dwordx4 v133, s[6:7]
	s_mov_b32 m0, s63
	s_nop 0
	global_load_lds_dwordx4 v135, s[6:7]
	s_waitcnt vmcnt(8)
	s_cmp_lg_u64 s[2:3], 0
	s_cbranch_scc1 .Lh0skip_8
	s_waitcnt lgkmcnt(0)
.Lh0skip_8:
	s_barrier
	s_waitcnt lgkmcnt(14)
	v_mfma_f32_16x16x32_bf16 v[124:127], v[128:131], v[156:159], v[124:127]
	v_mfma_f32_16x16x32_bf16 v[120:123], v[148:151], v[156:159], v[120:123]
	s_waitcnt lgkmcnt(13)
	v_mfma_f32_16x16x32_bf16 v[108:111], v[128:131], v[178:181], v[108:111]
	v_mfma_f32_16x16x32_bf16 v[104:107], v[148:151], v[178:181], v[104:107]
	s_waitcnt lgkmcnt(11)
	v_mfma_f32_16x16x32_bf16 v[92:95], v[128:131], v[186:189], v[92:95]
	v_mfma_f32_16x16x32_bf16 v[88:91], v[148:151], v[186:189], v[88:91]
	s_waitcnt lgkmcnt(9)
	v_mfma_f32_16x16x32_bf16 v[76:79], v[128:131], v[194:197], v[76:79]
	v_mfma_f32_16x16x32_bf16 v[72:75], v[148:151], v[194:197], v[72:75]
	s_waitcnt lgkmcnt(7)
	v_mfma_f32_16x16x32_bf16 v[60:63], v[128:131], v[202:205], v[60:63]
	v_mfma_f32_16x16x32_bf16 v[56:59], v[148:151], v[202:205], v[56:59]
	s_waitcnt lgkmcnt(5)
	v_mfma_f32_16x16x32_bf16 v[44:47], v[128:131], v[218:221], v[44:47]
	v_mfma_f32_16x16x32_bf16 v[40:43], v[148:151], v[218:221], v[40:43]
	s_waitcnt lgkmcnt(3)
	v_mfma_f32_16x16x32_bf16 v[28:31], v[128:131], v[226:229], v[28:31]
	v_mfma_f32_16x16x32_bf16 v[24:27], v[148:151], v[226:229], v[24:27]
	s_waitcnt lgkmcnt(1)
	v_mfma_f32_16x16x32_bf16 v[12:15], v[128:131], v[234:237], v[12:15]
	v_mfma_f32_16x16x32_bf16 v[8:11], v[148:151], v[234:237], v[8:11]
	v_mfma_f32_16x16x32_bf16 v[124:127], v[144:147], v[166:169], v[124:127]
	v_mfma_f32_16x16x32_bf16 v[120:123], v[152:155], v[166:169], v[120:123]
	v_mfma_f32_16x16x32_bf16 v[108:111], v[144:147], v[182:185], v[108:111]
	v_mfma_f32_16x16x32_bf16 v[104:107], v[152:155], v[182:185], v[104:107]
	v_mfma_f32_16x16x32_bf16 v[92:95], v[144:147], v[190:193], v[92:95]
	v_mfma_f32_16x16x32_bf16 v[88:91], v[152:155], v[190:193], v[88:91]
	v_mfma_f32_16x16x32_bf16 v[76:79], v[144:147], v[198:201], v[76:79]
	v_mfma_f32_16x16x32_bf16 v[72:75], v[152:155], v[198:201], v[72:75]
	v_mfma_f32_16x16x32_bf16 v[60:63], v[144:147], v[214:217], v[60:63]
	v_mfma_f32_16x16x32_bf16 v[56:59], v[152:155], v[214:217], v[56:59]
	v_mfma_f32_16x16x32_bf16 v[44:47], v[144:147], v[222:225], v[44:47]
	v_mfma_f32_16x16x32_bf16 v[40:43], v[152:155], v[222:225], v[40:43]
	v_mfma_f32_16x16x32_bf16 v[28:31], v[144:147], v[230:233], v[28:31]
	v_mfma_f32_16x16x32_bf16 v[24:27], v[152:155], v[230:233], v[24:27]
	s_waitcnt lgkmcnt(0)
	v_mfma_f32_16x16x32_bf16 v[12:15], v[144:147], v[238:241], v[12:15]
	v_mfma_f32_16x16x32_bf16 v[8:11], v[152:155], v[238:241], v[8:11]
	s_barrier
	ds_read_b128 v[128:131], v140
	ds_read_b128 v[144:147], v140 offset:1024
	ds_read_b128 v[148:151], v140 offset:2048
	ds_read_b128 v[152:155], v140 offset:3072
	s_mov_b32 m0, s48
	s_nop 0
	global_load_lds_dwordx4 v133, s[82:83]
	s_mov_b32 m0, s49
	s_nop 0
	global_load_lds_dwordx4 v135, s[82:83]
	s_mov_b32 m0, s47
	s_nop 0
	global_load_lds_dwordx4 v132, s[38:39]
	s_mov_b32 m0, s50
	s_nop 0
	global_load_lds_dwordx4 v134, s[38:39]
	s_add_u32 s88, s38, 0x40000
	s_addc_u32 s89, s39, 0
	s_mov_b32 m0, s51
	s_nop 0
	global_load_lds_dwordx4 v132, s[88:89]
	s_mov_b32 m0, s52
	s_nop 0
	global_load_lds_dwordx4 v134, s[88:89]
	s_waitcnt vmcnt(8)
	s_cmp_lg_u64 s[2:3], 0
	s_cbranch_scc1 .Lh0skip_9
	s_waitcnt lgkmcnt(0)
; #define PG8_STAGE(bufoff, gbase, voff) do { _Pragma("unroll") for (int _i = 0; _i < 2; ++_i) { \
;         const unsigned _m0 = ldsu + (unsigned)(bufoff) + ldsw + (unsigned)(_i * 8192); \
;         asm volatile("s_mov_b32 m0, %2\n\ts_nop 0\n\tglobal_load_lds_dwordx4 %0, %1" :: "v"((voff)[_i]), "s"((const char*)(gbase)), "s"(_m0) : "memory"); } } while (0)
; #define PG8_LDA(dst, b, h) do { _Pragma("unroll") for (int m = 0; m < 4; ++m) _Pragma("unroll") for (int k = 0; k < 2; ++k) dst[m][k] = *(const LAS bf16x8*)(lds + PG8_SA(b, h) + aoff + m * 2048 + k * 1024); } while (0)
; #define PG8_LDB(dst, b, h) do { _Pragma("unroll") for (int n = 0; n < 2; ++n) _Pragma("unroll") for (int k = 0; k < 2; ++k) dst[n][k] = *(const LAS bf16x8*)(lds + bbase[b][h] + n * 2048 + k * 1024); } while (0)
; #define PG8_WAIT_V(n) asm volatile("s_waitcnt vmcnt(" #n ")" ::: "memory")
; #define PG8_WAIT_L(n) asm volatile("s_waitcnt lgkmcnt(" #n ")" ::: "memory")
; #define PG8_BAR __builtin_amdgcn_s_barrier()
; #define PG8_SCHED __builtin_amdgcn_sched_barrier(0)
; template <class Epi>
; __device__ __forceinline__ void gemm_phase(LAS unsigned char* lds, const Gemm g, const StaticOrder& S, const Epi& E) {
;     ...
;             PG8_WAIT_V(8); PG8_WAIT_L(0); PG8_BAR; PG8_MMA2B(1, At, At2, B0); PG8_BAR; PG8_SCHED;
;             PG8_LDB(B0, 1, 0); PG8_SCHED; PG8_LDA(At, 1, 0); PG8_LDA(At2, 1, 1); PG8_STAGE(PG8_SB(0, 1), b2 + hstepB, voffB);
;             PG8_WAIT_V(8); PG8_WAIT_L(0); PG8_BAR; PG8_MMA2B(0, At, At2, B0); PG8_BAR; PG8_SCHED;
.Lh0skip_9:
	s_barrier
	s_waitcnt lgkmcnt(3)
	v_mfma_f32_16x16x32_bf16 v[116:119], v[128:131], v[156:159], v[116:119]
	s_waitcnt lgkmcnt(1)
	v_mfma_f32_16x16x32_bf16 v[112:115], v[148:151], v[156:159], v[112:115]
	v_mfma_f32_16x16x32_bf16 v[100:103], v[128:131], v[178:181], v[100:103]
	v_mfma_f32_16x16x32_bf16 v[96:99], v[148:151], v[178:181], v[96:99]
	v_mfma_f32_16x16x32_bf16 v[84:87], v[128:131], v[186:189], v[84:87]
	v_mfma_f32_16x16x32_bf16 v[80:83], v[148:151], v[186:189], v[80:83]
	v_mfma_f32_16x16x32_bf16 v[68:71], v[128:131], v[194:197], v[68:71]
	v_mfma_f32_16x16x32_bf16 v[64:67], v[148:151], v[194:197], v[64:67]
	v_mfma_f32_16x16x32_bf16 v[52:55], v[128:131], v[202:205], v[52:55]
	v_mfma_f32_16x16x32_bf16 v[48:51], v[148:151], v[202:205], v[48:51]
	v_mfma_f32_16x16x32_bf16 v[36:39], v[128:131], v[218:221], v[36:39]
	v_mfma_f32_16x16x32_bf16 v[32:35], v[148:151], v[218:221], v[32:35]
	v_mfma_f32_16x16x32_bf16 v[20:23], v[128:131], v[226:229], v[20:23]
	v_mfma_f32_16x16x32_bf16 v[16:19], v[148:151], v[226:229], v[16:19]
	v_mfma_f32_16x16x32_bf16 v[4:7], v[128:131], v[234:237], v[4:7]
	v_mfma_f32_16x16x32_bf16 v[0:3], v[148:151], v[234:237], v[0:3]
	v_mfma_f32_16x16x32_bf16 v[116:119], v[144:147], v[166:169], v[116:119]
	s_waitcnt lgkmcnt(0)
	v_mfma_f32_16x16x32_bf16 v[112:115], v[152:155], v[166:169], v[112:115]
	v_mfma_f32_16x16x32_bf16 v[100:103], v[144:147], v[182:185], v[100:103]
	v_mfma_f32_16x16x32_bf16 v[96:99], v[152:155], v[182:185], v[96:99]
	v_mfma_f32_16x16x32_bf16 v[84:87], v[144:147], v[190:193], v[84:87]
	v_mfma_f32_16x16x32_bf16 v[80:83], v[152:155], v[190:193], v[80:83]
	v_mfma_f32_16x16x32_bf16 v[68:71], v[144:147], v[198:201], v[68:71]
	v_mfma_f32_16x16x32_bf16 v[64:67], v[152:155], v[198:201], v[64:67]
	v_mfma_f32_16x16x32_bf16 v[52:55], v[144:147], v[214:217], v[52:55]
	v_mfma_f32_16x16x32_bf16 v[48:51], v[152:155], v[214:217], v[48:51]
	v_mfma_f32_16x16x32_bf16 v[36:39], v[144:147], v[222:225], v[36:39]
	v_mfma_f32_16x16x32_bf16 v[32:35], v[152:155], v[222:225], v[32:35]
	v_mfma_f32_16x16x32_bf16 v[20:23], v[144:147], v[230:233], v[20:23]
	v_mfma_f32_16x16x32_bf16 v[16:19], v[152:155], v[230:233], v[16:19]
	v_mfma_f32_16x16x32_bf16 v[4:7], v[144:147], v[238:241], v[4:7]
	v_mfma_f32_16x16x32_bf16 v[0:3], v[152:155], v[238:241], v[0:3]
	s_barrier
	ds_read_b128 v[128:131], v141
	ds_read_b128 v[144:147], v141 offset:1024
	ds_read_b128 v[148:151], v141 offset:2048
	ds_read_b128 v[152:155], v141 offset:3072
	ds_read_b128 v[156:159], v139 offset:32768
	ds_read_b128 v[166:169], v139 offset:33792
	ds_read_b128 v[178:181], v139 offset:34816
	ds_read_b128 v[182:185], v139 offset:35840
	ds_read_b128 v[186:189], v139 offset:36864
	ds_read_b128 v[190:193], v139 offset:37888
	ds_read_b128 v[194:197], v139 offset:38912
	ds_read_b128 v[198:201], v139 offset:39936
	ds_read_b128 v[202:205], v139 offset:49152
	ds_read_b128 v[214:217], v139 offset:50176
	ds_read_b128 v[218:221], v139 offset:51200
	ds_read_b128 v[222:225], v139 offset:52224
	ds_read_b128 v[226:229], v139 offset:53248
	ds_read_b128 v[230:233], v139 offset:54272
	ds_read_b128 v[234:237], v139 offset:55296
	ds_read_b128 v[238:241], v139 offset:56320
	s_add_u32 s82, s82, 0x40000
	s_addc_u32 s83, s83, 0
	s_mov_b32 m0, s53
	s_nop 0
	global_load_lds_dwordx4 v133, s[82:83]
	s_mov_b32 m0, s54
	s_nop 0
	global_load_lds_dwordx4 v135, s[82:83]
	s_waitcnt vmcnt(8)
	s_cmp_lg_u64 s[2:3], 0
	s_cbranch_scc1 .Lh0skip_10
	s_waitcnt lgkmcnt(0)
; #define PG8_STAGE(bufoff, gbase, voff) do { _Pragma("unroll") for (int _i = 0; _i < 2; ++_i) { \
;         const unsigned _m0 = ldsu + (unsigned)(bufoff) + ldsw + (unsigned)(_i * 8192); \
;         asm volatile("s_mov_b32 m0, %2\n\ts_nop 0\n\tglobal_load_lds_dwordx4 %0, %1" :: "v"((voff)[_i]), "s"((const char*)(gbase)), "s"(_m0) : "memory"); } } while (0)
; #define PG8_LDB(dst, b, h) do { _Pragma("unroll") for (int n = 0; n < 2; ++n) _Pragma("unroll") for (int k = 0; k < 2; ++k) dst[n][k] = *(const LAS bf16x8*)(lds + bbase[b][h] + n * 2048 + k * 1024); } while (0)
; #define PG8_WAIT_V(n) asm volatile("s_waitcnt vmcnt(" #n ")" ::: "memory")
; #define PG8_WAIT_L(n) asm volatile("s_waitcnt lgkmcnt(" #n ")" ::: "memory")
; #define PG8_BAR __builtin_amdgcn_s_barrier()
; #define PG8_SCHED __builtin_amdgcn_sched_barrier(0)
; template <class Epi>
; __device__ __forceinline__ void gemm_phase(LAS unsigned char* lds, const Gemm g, const StaticOrder& S, const Epi& E) {
;     ...
;             PG8_WAIT_V(8); PG8_WAIT_L(0); PG8_BAR; PG8_MMA2B(0, At, At2, B0); PG8_BAR; PG8_SCHED;
;             PG8_LDB(B0, 1, 1); PG8_STAGE(PG8_SB(1, 0), b3, voffB); PG8_STAGE(PG8_SA(1, 0), a3, voffA); PG8_STAGE(PG8_SA(1, 1), a3 + hstepA, voffA);
;             PG8_WAIT_V(8); PG8_WAIT_L(0); PG8_BAR; PG8_MMA2B(1, At, At2, B0); PG8_BAR; PG8_SCHED;
;         }
;         if (wr == 0) PG8_BAR;
.Lh0skip_10:
	s_barrier
	s_waitcnt lgkmcnt(14)
	v_mfma_f32_16x16x32_bf16 v[124:127], v[128:131], v[156:159], v[124:127]
	v_mfma_f32_16x16x32_bf16 v[120:123], v[148:151], v[156:159], v[120:123]
	s_waitcnt lgkmcnt(13)
	v_mfma_f32_16x16x32_bf16 v[108:111], v[128:131], v[178:181], v[108:111]
	v_mfma_f32_16x16x32_bf16 v[104:107], v[148:151], v[178:181], v[104:107]
	s_waitcnt lgkmcnt(11)
	v_mfma_f32_16x16x32_bf16 v[92:95], v[128:131], v[186:189], v[92:95]
	v_mfma_f32_16x16x32_bf16 v[88:91], v[148:151], v[186:189], v[88:91]
	s_waitcnt lgkmcnt(9)
	v_mfma_f32_16x16x32_bf16 v[76:79], v[128:131], v[194:197], v[76:79]
	v_mfma_f32_16x16x32_bf16 v[72:75], v[148:151], v[194:197], v[72:75]
	s_waitcnt lgkmcnt(7)
	v_mfma_f32_16x16x32_bf16 v[60:63], v[128:131], v[202:205], v[60:63]
	v_mfma_f32_16x16x32_bf16 v[56:59], v[148:151], v[202:205], v[56:59]
	s_waitcnt lgkmcnt(5)
	v_mfma_f32_16x16x32_bf16 v[44:47], v[128:131], v[218:221], v[44:47]
	v_mfma_f32_16x16x32_bf16 v[40:43], v[148:151], v[218:221], v[40:43]
	s_waitcnt lgkmcnt(3)
	v_mfma_f32_16x16x32_bf16 v[28:31], v[128:131], v[226:229], v[28:31]
	v_mfma_f32_16x16x32_bf16 v[24:27], v[148:151], v[226:229], v[24:27]
	s_waitcnt lgkmcnt(1)
	v_mfma_f32_16x16x32_bf16 v[12:15], v[128:131], v[234:237], v[12:15]
	v_mfma_f32_16x16x32_bf16 v[8:11], v[148:151], v[234:237], v[8:11]
	v_mfma_f32_16x16x32_bf16 v[124:127], v[144:147], v[166:169], v[124:127]
	v_mfma_f32_16x16x32_bf16 v[120:123], v[152:155], v[166:169], v[120:123]
	v_mfma_f32_16x16x32_bf16 v[108:111], v[144:147], v[182:185], v[108:111]
	v_mfma_f32_16x16x32_bf16 v[104:107], v[152:155], v[182:185], v[104:107]
	v_mfma_f32_16x16x32_bf16 v[92:95], v[144:147], v[190:193], v[92:95]
	v_mfma_f32_16x16x32_bf16 v[88:91], v[152:155], v[190:193], v[88:91]
	v_mfma_f32_16x16x32_bf16 v[76:79], v[144:147], v[198:201], v[76:79]
	v_mfma_f32_16x16x32_bf16 v[72:75], v[152:155], v[198:201], v[72:75]
	v_mfma_f32_16x16x32_bf16 v[60:63], v[144:147], v[214:217], v[60:63]
	v_mfma_f32_16x16x32_bf16 v[56:59], v[152:155], v[214:217], v[56:59]
	v_mfma_f32_16x16x32_bf16 v[44:47], v[144:147], v[222:225], v[44:47]
	v_mfma_f32_16x16x32_bf16 v[40:43], v[152:155], v[222:225], v[40:43]
	v_mfma_f32_16x16x32_bf16 v[28:31], v[144:147], v[230:233], v[28:31]
	v_mfma_f32_16x16x32_bf16 v[24:27], v[152:155], v[230:233], v[24:27]
	s_waitcnt lgkmcnt(0)
	v_mfma_f32_16x16x32_bf16 v[12:15], v[144:147], v[238:241], v[12:15]
	v_mfma_f32_16x16x32_bf16 v[8:11], v[152:155], v[238:241], v[8:11]
	s_barrier
	ds_read_b128 v[128:131], v142
	ds_read_b128 v[144:147], v142 offset:1024
	ds_read_b128 v[148:151], v142 offset:2048
	ds_read_b128 v[152:155], v142 offset:3072
	s_mov_b32 m0, s55
	s_nop 0
	global_load_lds_dwordx4 v133, s[80:81]
	s_mov_b32 m0, s56
	s_nop 0
	global_load_lds_dwordx4 v135, s[80:81]
	s_mov_b32 m0, s57
	s_nop 0
	global_load_lds_dwordx4 v132, s[42:43]
	s_mov_b32 m0, s58
	s_nop 0
	global_load_lds_dwordx4 v134, s[42:43]
	s_add_u32 s38, s38, 0x40080
	s_addc_u32 s39, s39, 0
	s_mov_b32 m0, s59
	s_nop 0
	global_load_lds_dwordx4 v132, s[38:39]
	s_mov_b32 m0, s60
	s_nop 0
	global_load_lds_dwordx4 v134, s[38:39]
	s_waitcnt vmcnt(8)
	s_cmp_lg_u64 s[2:3], 0
	s_cbranch_scc1 .Lh0skip_11
	s_waitcnt lgkmcnt(0)
.Lh0skip_11:
	s_barrier
	s_waitcnt lgkmcnt(3)
	v_mfma_f32_16x16x32_bf16 v[116:119], v[128:131], v[156:159], v[116:119]
	s_waitcnt lgkmcnt(1)
	v_mfma_f32_16x16x32_bf16 v[112:115], v[148:151], v[156:159], v[112:115]
	v_mfma_f32_16x16x32_bf16 v[100:103], v[128:131], v[178:181], v[100:103]
	v_mfma_f32_16x16x32_bf16 v[96:99], v[148:151], v[178:181], v[96:99]
	v_mfma_f32_16x16x32_bf16 v[84:87], v[128:131], v[186:189], v[84:87]
	v_mfma_f32_16x16x32_bf16 v[80:83], v[148:151], v[186:189], v[80:83]
	v_mfma_f32_16x16x32_bf16 v[68:71], v[128:131], v[194:197], v[68:71]
	v_mfma_f32_16x16x32_bf16 v[64:67], v[148:151], v[194:197], v[64:67]
	v_mfma_f32_16x16x32_bf16 v[52:55], v[128:131], v[202:205], v[52:55]
	v_mfma_f32_16x16x32_bf16 v[48:51], v[148:151], v[202:205], v[48:51]
	v_mfma_f32_16x16x32_bf16 v[36:39], v[128:131], v[218:221], v[36:39]
	v_mfma_f32_16x16x32_bf16 v[32:35], v[148:151], v[218:221], v[32:35]
	v_mfma_f32_16x16x32_bf16 v[20:23], v[128:131], v[226:229], v[20:23]
	v_mfma_f32_16x16x32_bf16 v[16:19], v[148:151], v[226:229], v[16:19]
	v_mfma_f32_16x16x32_bf16 v[4:7], v[128:131], v[234:237], v[4:7]
	v_mfma_f32_16x16x32_bf16 v[0:3], v[148:151], v[234:237], v[0:3]
	v_mfma_f32_16x16x32_bf16 v[116:119], v[144:147], v[166:169], v[116:119]
	s_waitcnt lgkmcnt(0)
	v_mfma_f32_16x16x32_bf16 v[112:115], v[152:155], v[166:169], v[112:115]
	v_mfma_f32_16x16x32_bf16 v[100:103], v[144:147], v[182:185], v[100:103]
	v_mfma_f32_16x16x32_bf16 v[96:99], v[152:155], v[182:185], v[96:99]
	v_mfma_f32_16x16x32_bf16 v[84:87], v[144:147], v[190:193], v[84:87]
	v_mfma_f32_16x16x32_bf16 v[80:83], v[152:155], v[190:193], v[80:83]
	v_mfma_f32_16x16x32_bf16 v[68:71], v[144:147], v[198:201], v[68:71]
	v_mfma_f32_16x16x32_bf16 v[64:67], v[152:155], v[198:201], v[64:67]
	v_mfma_f32_16x16x32_bf16 v[52:55], v[144:147], v[214:217], v[52:55]
	v_mfma_f32_16x16x32_bf16 v[48:51], v[152:155], v[214:217], v[48:51]
	v_mfma_f32_16x16x32_bf16 v[36:39], v[144:147], v[222:225], v[36:39]
	v_mfma_f32_16x16x32_bf16 v[32:35], v[152:155], v[222:225], v[32:35]
	v_mfma_f32_16x16x32_bf16 v[20:23], v[144:147], v[230:233], v[20:23]
	v_mfma_f32_16x16x32_bf16 v[16:19], v[152:155], v[230:233], v[16:19]
	v_mfma_f32_16x16x32_bf16 v[4:7], v[144:147], v[238:241], v[4:7]
	v_mfma_f32_16x16x32_bf16 v[0:3], v[152:155], v[238:241], v[0:3]
	s_barrier
	s_add_i32 s68, s68, 2
	s_add_u32 s6, s6, 0x100
	s_addc_u32 s7, s7, 0
	s_add_u32 s84, s84, 0x100
	s_addc_u32 s85, s85, 0
	s_add_u32 s86, s86, 0x100
	s_addc_u32 s87, s87, 0
	s_cmp_gt_u32 s68, 13
	s_cbranch_scc0 .LBB0_943
	s_and_b64 vcc, exec, s[2:3]
	s_cbranch_vccz .LBB0_946
	s_barrier

; #define PG8_STAGE(bufoff, gbase, voff) do { _Pragma("unroll") for (int _i = 0; _i < 2; ++_i) { \
;         const unsigned _m0 = ldsu + (unsigned)(bufoff) + ldsw + (unsigned)(_i * 8192); \
;         asm volatile("s_mov_b32 m0, %2\n\ts_nop 0\n\tglobal_load_lds_dwordx4 %0, %1" :: "v"((voff)[_i]), "s"((const char*)(gbase)), "s"(_m0) : "memory"); } } while (0)
; #define PG8_LDA(dst, b, h) do { _Pragma("unroll") for (int m = 0; m < 4; ++m) _Pragma("unroll") for (int k = 0; k < 2; ++k) dst[m][k] = *(const LAS bf16x8*)(lds + PG8_SA(b, h) + aoff + m * 2048 + k * 1024); } while (0)
; #define PG8_LDB(dst, b, h) do { _Pragma("unroll") for (int n = 0; n < 2; ++n) _Pragma("unroll") for (int k = 0; k < 2; ++k) dst[n][k] = *(const LAS bf16x8*)(lds + bbase[b][h] + n * 2048 + k * 1024); } while (0)
; #define PG8_WAIT_V(n) asm volatile("s_waitcnt vmcnt(" #n ")" ::: "memory")
; #define PG8_WAIT_L(n) asm volatile("s_waitcnt lgkmcnt(" #n ")" ::: "memory")
; #define PG8_BAR __builtin_amdgcn_s_barrier()
; #define PG8_SCHED __builtin_amdgcn_sched_barrier(0)
; template <class Epi>
; __device__ __forceinline__ void gemm_phase(LAS unsigned char* lds, const Gemm g, const StaticOrder& S, const Epi& E) {
;     ...
;             const bool last = (t == nt - 2);
;             const char* a2 = last ? nA : cA + (size_t)(t + 2) * kstep; const char* b2 = last ? nB : cB + (size_t)(t + 2) * kstep;
;             const char* a3 = a2 + kstep; const char* b3 = b2 + kstep;
;             const char* b1 = cB + (size_t)(t + 1) * kstep;
;             PG8_LDB(B0, 0, 0); PG8_SCHED; PG8_LDA(At, 0, 0); PG8_LDA(At2, 0, 1); PG8_STAGE(PG8_SB(1, 1), b1 + hstepB, voffB);
;             PG8_WAIT_V(8); PG8_WAIT_L(0); PG8_BAR; PG8_MMA2B(0, At, At2, B0); PG8_BAR; PG8_SCHED;
;             PG8_LDB(B0, 0, 1); PG8_STAGE(PG8_SB(0, 0), b2, voffB); PG8_STAGE(PG8_SA(0, 0), a2, voffA); PG8_STAGE(PG8_SA(0, 1), a2 + hstepA, voffA);
;             PG8_WAIT_V(8); PG8_WAIT_L(0); PG8_BAR; PG8_MMA2B(1, At, At2, B0); PG8_BAR; PG8_SCHED;
.LBB0_1027:
	ds_read_b128 v[68:71], v220
	ds_read_b128 v[84:87], v220 offset:1024
	ds_read_b128 v[88:91], v220 offset:2048
	ds_read_b128 v[92:95], v220 offset:3072
	s_add_u32 s12, s10, 0x100
	s_addc_u32 s13, s11, 0
	s_cmp_eq_u32 s69, 12
	s_cselect_b32 s14, s97, vcc_hi
	s_cselect_b32 s15, s7, s68
	s_cselect_b32 s84, vcc_lo, s12
	s_cselect_b32 s85, s39, s13
	s_add_u32 s16, s14, 0x80
	s_addc_u32 s17, s15, 0
	ds_read_b128 v[96:99], v221
	ds_read_b128 v[100:103], v221 offset:1024
	ds_read_b128 v[152:155], v221 offset:2048
	ds_read_b128 v[156:159], v221 offset:3072
	ds_read_b128 v[166:169], v221 offset:4096
	ds_read_b128 v[178:181], v221 offset:5120
	ds_read_b128 v[182:185], v221 offset:6144
	ds_read_b128 v[186:189], v221 offset:7168
	ds_read_b128 v[190:193], v221 offset:16384
	ds_read_b128 v[194:197], v221 offset:17408
	ds_read_b128 v[198:201], v221 offset:18432
	ds_read_b128 v[202:205], v221 offset:19456
	ds_read_b128 v[226:229], v221 offset:20480
	ds_read_b128 v[230:233], v221 offset:21504
	ds_read_b128 v[234:237], v221 offset:22528
	ds_read_b128 v[238:241], v221 offset:23552
	s_add_u32 s10, s10, 0x40080
	s_addc_u32 s11, s11, 0
	s_mov_b32 m0, s58
	s_nop 0
	global_load_lds_dwordx4 v217, s[10:11]
	s_mov_b32 m0, s60
	s_nop 0
	global_load_lds_dwordx4 v219, s[10:11]
	s_waitcnt vmcnt(8)
	s_cmp_lg_u64 s[90:91], 0
	s_cbranch_scc1 .Lh0skip_12
	s_waitcnt lgkmcnt(0)
.Lh0skip_12:
	s_barrier
	s_waitcnt lgkmcnt(14)
	v_mfma_f32_16x16x32_bf16 v[80:83], v[68:71], v[96:99], v[80:83]
	v_mfma_f32_16x16x32_bf16 v[76:79], v[88:91], v[96:99], v[76:79]
	s_waitcnt lgkmcnt(13)
	v_mfma_f32_16x16x32_bf16 v[148:151], v[68:71], v[152:155], v[148:151]
	v_mfma_f32_16x16x32_bf16 v[52:55], v[88:91], v[152:155], v[52:55]
	s_waitcnt lgkmcnt(11)
	v_mfma_f32_16x16x32_bf16 v[144:147], v[68:71], v[166:169], v[144:147]
	v_mfma_f32_16x16x32_bf16 v[48:51], v[88:91], v[166:169], v[48:51]
	s_waitcnt lgkmcnt(9)
	v_mfma_f32_16x16x32_bf16 v[136:139], v[68:71], v[182:185], v[136:139]
	v_mfma_f32_16x16x32_bf16 v[40:43], v[88:91], v[182:185], v[40:43]
	s_waitcnt lgkmcnt(7)
	v_mfma_f32_16x16x32_bf16 v[124:127], v[68:71], v[190:193], v[124:127]
	v_mfma_f32_16x16x32_bf16 v[28:31], v[88:91], v[190:193], v[28:31]
	s_waitcnt lgkmcnt(5)
	v_mfma_f32_16x16x32_bf16 v[120:123], v[68:71], v[198:201], v[120:123]
	v_mfma_f32_16x16x32_bf16 v[24:27], v[88:91], v[198:201], v[24:27]
	s_waitcnt lgkmcnt(3)
	v_mfma_f32_16x16x32_bf16 v[112:115], v[68:71], v[226:229], v[112:115]
	v_mfma_f32_16x16x32_bf16 v[16:19], v[88:91], v[226:229], v[16:19]
	s_waitcnt lgkmcnt(1)
	v_mfma_f32_16x16x32_bf16 v[64:67], v[68:71], v[234:237], v[64:67]
	v_mfma_f32_16x16x32_bf16 v[4:7], v[88:91], v[234:237], v[4:7]
	v_mfma_f32_16x16x32_bf16 v[80:83], v[84:87], v[100:103], v[80:83]
	v_mfma_f32_16x16x32_bf16 v[76:79], v[92:95], v[100:103], v[76:79]
	v_mfma_f32_16x16x32_bf16 v[148:151], v[84:87], v[156:159], v[148:151]
	v_mfma_f32_16x16x32_bf16 v[52:55], v[92:95], v[156:159], v[52:55]
	v_mfma_f32_16x16x32_bf16 v[144:147], v[84:87], v[178:181], v[144:147]
	v_mfma_f32_16x16x32_bf16 v[48:51], v[92:95], v[178:181], v[48:51]
	v_mfma_f32_16x16x32_bf16 v[136:139], v[84:87], v[186:189], v[136:139]
	v_mfma_f32_16x16x32_bf16 v[40:43], v[92:95], v[186:189], v[40:43]
	v_mfma_f32_16x16x32_bf16 v[124:127], v[84:87], v[194:197], v[124:127]
	v_mfma_f32_16x16x32_bf16 v[28:31], v[92:95], v[194:197], v[28:31]
	v_mfma_f32_16x16x32_bf16 v[120:123], v[84:87], v[202:205], v[120:123]
	v_mfma_f32_16x16x32_bf16 v[24:27], v[92:95], v[202:205], v[24:27]
	v_mfma_f32_16x16x32_bf16 v[112:115], v[84:87], v[230:233], v[112:115]
	v_mfma_f32_16x16x32_bf16 v[16:19], v[92:95], v[230:233], v[16:19]
	s_waitcnt lgkmcnt(0)
	v_mfma_f32_16x16x32_bf16 v[64:67], v[84:87], v[238:241], v[64:67]
	v_mfma_f32_16x16x32_bf16 v[4:7], v[92:95], v[238:241], v[4:7]
	s_barrier
	ds_read_b128 v[68:71], v222
	ds_read_b128 v[84:87], v222 offset:1024
	ds_read_b128 v[88:91], v222 offset:2048
	ds_read_b128 v[92:95], v222 offset:3072
	s_mov_b32 m0, s48
	s_nop 0
	global_load_lds_dwordx4 v217, s[84:85]
	s_mov_b32 m0, s49
	s_nop 0
	global_load_lds_dwordx4 v219, s[84:85]
	s_mov_b32 m0, s47
	s_nop 0
	global_load_lds_dwordx4 v216, s[14:15]
	s_mov_b32 m0, s50
	s_nop 0
	global_load_lds_dwordx4 v218, s[14:15]
	s_add_u32 s10, s14, 0x40000
	s_addc_u32 s11, s15, 0
	s_mov_b32 m0, s51
	s_nop 0
	global_load_lds_dwordx4 v216, s[10:11]
	s_mov_b32 m0, s52
	s_nop 0
	global_load_lds_dwordx4 v218, s[10:11]
	s_waitcnt vmcnt(8)
	s_cmp_lg_u64 s[90:91], 0
	s_cbranch_scc1 .Lh0skip_13
	s_waitcnt lgkmcnt(0)
; #define PG8_STAGE(bufoff, gbase, voff) do { _Pragma("unroll") for (int _i = 0; _i < 2; ++_i) { \
;         const unsigned _m0 = ldsu + (unsigned)(bufoff) + ldsw + (unsigned)(_i * 8192); \
;         asm volatile("s_mov_b32 m0, %2\n\ts_nop 0\n\tglobal_load_lds_dwordx4 %0, %1" :: "v"((voff)[_i]), "s"((const char*)(gbase)), "s"(_m0) : "memory"); } } while (0)
; #define PG8_LDA(dst, b, h) do { _Pragma("unroll") for (int m = 0; m < 4; ++m) _Pragma("unroll") for (int k = 0; k < 2; ++k) dst[m][k] = *(const LAS bf16x8*)(lds + PG8_SA(b, h) + aoff + m * 2048 + k * 1024); } while (0)
; #define PG8_LDB(dst, b, h) do { _Pragma("unroll") for (int n = 0; n < 2; ++n) _Pragma("unroll") for (int k = 0; k < 2; ++k) dst[n][k] = *(const LAS bf16x8*)(lds + bbase[b][h] + n * 2048 + k * 1024); } while (0)
; #define PG8_WAIT_V(n) asm volatile("s_waitcnt vmcnt(" #n ")" ::: "memory")
; #define PG8_WAIT_L(n) asm volatile("s_waitcnt lgkmcnt(" #n ")" ::: "memory")
; #define PG8_BAR __builtin_amdgcn_s_barrier()
; #define PG8_SCHED __builtin_amdgcn_sched_barrier(0)
; template <class Epi>
; __device__ __forceinline__ void gemm_phase(LAS unsigned char* lds, const Gemm g, const StaticOrder& S, const Epi& E) {
;     ...
;             PG8_WAIT_V(8); PG8_WAIT_L(0); PG8_BAR; PG8_MMA2B(1, At, At2, B0); PG8_BAR; PG8_SCHED;
;             PG8_LDB(B0, 1, 0); PG8_SCHED; PG8_LDA(At, 1, 0); PG8_LDA(At2, 1, 1); PG8_STAGE(PG8_SB(0, 1), b2 + hstepB, voffB);
;             PG8_WAIT_V(8); PG8_WAIT_L(0); PG8_BAR; PG8_MMA2B(0, At, At2, B0); PG8_BAR; PG8_SCHED;
.Lh0skip_13:
	s_barrier
	s_waitcnt lgkmcnt(3)
	v_mfma_f32_16x16x32_bf16 v[72:75], v[68:71], v[96:99], v[72:75]
	s_waitcnt lgkmcnt(1)
	v_mfma_f32_16x16x32_bf16 v[56:59], v[88:91], v[96:99], v[56:59]
	v_mfma_f32_16x16x32_bf16 v[44:47], v[88:91], v[152:155], v[44:47]
	v_mfma_f32_16x16x32_bf16 v[36:39], v[88:91], v[166:169], v[36:39]
	v_mfma_f32_16x16x32_bf16 v[128:131], v[68:71], v[182:185], v[128:131]
	v_mfma_f32_16x16x32_bf16 v[32:35], v[88:91], v[182:185], v[32:35]
	v_mfma_f32_16x16x32_bf16 v[116:119], v[68:71], v[190:193], v[116:119]
	v_mfma_f32_16x16x32_bf16 v[20:23], v[88:91], v[190:193], v[20:23]
	v_mfma_f32_16x16x32_bf16 v[108:111], v[68:71], v[198:201], v[108:111]
	v_mfma_f32_16x16x32_bf16 v[12:15], v[88:91], v[198:201], v[12:15]
	v_mfma_f32_16x16x32_bf16 v[104:107], v[68:71], v[226:229], v[104:107]
	v_mfma_f32_16x16x32_bf16 v[8:11], v[88:91], v[226:229], v[8:11]
	v_mfma_f32_16x16x32_bf16 v[60:63], v[68:71], v[234:237], v[60:63]
	v_mfma_f32_16x16x32_bf16 v[0:3], v[88:91], v[234:237], v[0:3]
	v_mfma_f32_16x16x32_bf16 v[72:75], v[84:87], v[100:103], v[72:75]
	s_waitcnt lgkmcnt(0)
	v_mfma_f32_16x16x32_bf16 v[56:59], v[92:95], v[100:103], v[56:59]
	v_mfma_f32_16x16x32_bf16 v[96:99], v[68:71], v[152:155], v[140:143]
	v_mfma_f32_16x16x32_bf16 v[44:47], v[92:95], v[156:159], v[44:47]
	v_mfma_f32_16x16x32_bf16 v[100:103], v[68:71], v[166:169], v[132:135]
	v_mfma_f32_16x16x32_bf16 v[36:39], v[92:95], v[178:181], v[36:39]
	v_mfma_f32_16x16x32_bf16 v[128:131], v[84:87], v[186:189], v[128:131]
	v_mfma_f32_16x16x32_bf16 v[32:35], v[92:95], v[186:189], v[32:35]
	v_mfma_f32_16x16x32_bf16 v[116:119], v[84:87], v[194:197], v[116:119]
	v_mfma_f32_16x16x32_bf16 v[20:23], v[92:95], v[194:197], v[20:23]
	v_mfma_f32_16x16x32_bf16 v[108:111], v[84:87], v[202:205], v[108:111]
	v_mfma_f32_16x16x32_bf16 v[12:15], v[92:95], v[202:205], v[12:15]
	v_mfma_f32_16x16x32_bf16 v[104:107], v[84:87], v[230:233], v[104:107]
	v_mfma_f32_16x16x32_bf16 v[8:11], v[92:95], v[230:233], v[8:11]
	v_mfma_f32_16x16x32_bf16 v[60:63], v[84:87], v[238:241], v[60:63]
	v_mfma_f32_16x16x32_bf16 v[0:3], v[92:95], v[238:241], v[0:3]
	v_mfma_f32_16x16x32_bf16 v[96:99], v[84:87], v[156:159], v[96:99]
	v_mfma_f32_16x16x32_bf16 v[100:103], v[84:87], v[178:181], v[100:103]
	s_barrier
	ds_read_b128 v[68:71], v223
	ds_read_b128 v[84:87], v223 offset:1024
	ds_read_b128 v[88:91], v223 offset:2048
	ds_read_b128 v[92:95], v223 offset:3072
	ds_read_b128 v[132:135], v221 offset:32768
	ds_read_b128 v[140:143], v221 offset:33792
	ds_read_b128 v[152:155], v221 offset:34816
	ds_read_b128 v[156:159], v221 offset:35840
	ds_read_b128 v[166:169], v221 offset:36864
	ds_read_b128 v[178:181], v221 offset:37888
	ds_read_b128 v[182:185], v221 offset:38912
	ds_read_b128 v[186:189], v221 offset:39936
	ds_read_b128 v[190:193], v221 offset:49152
	ds_read_b128 v[194:197], v221 offset:50176
	ds_read_b128 v[198:201], v221 offset:51200
	ds_read_b128 v[202:205], v221 offset:52224
	ds_read_b128 v[226:229], v221 offset:53248
	ds_read_b128 v[230:233], v221 offset:54272
	ds_read_b128 v[234:237], v221 offset:55296
	ds_read_b128 v[238:241], v221 offset:56320
	s_add_u32 s10, s84, 0x40000
	s_addc_u32 s11, s85, 0
	s_mov_b32 m0, s53
	s_nop 0
	global_load_lds_dwordx4 v217, s[10:11]
	s_mov_b32 m0, s54
	s_nop 0
	global_load_lds_dwordx4 v219, s[10:11]
	s_waitcnt vmcnt(8)
	s_cmp_lg_u64 s[90:91], 0
	s_cbranch_scc1 .Lh0skip_14
	s_waitcnt lgkmcnt(0)
; #define PG8_STAGE(bufoff, gbase, voff) do { _Pragma("unroll") for (int _i = 0; _i < 2; ++_i) { \
;         const unsigned _m0 = ldsu + (unsigned)(bufoff) + ldsw + (unsigned)(_i * 8192); \
;         asm volatile("s_mov_b32 m0, %2\n\ts_nop 0\n\tglobal_load_lds_dwordx4 %0, %1" :: "v"((voff)[_i]), "s"((const char*)(gbase)), "s"(_m0) : "memory"); } } while (0)
; #define PG8_LDB(dst, b, h) do { _Pragma("unroll") for (int n = 0; n < 2; ++n) _Pragma("unroll") for (int k = 0; k < 2; ++k) dst[n][k] = *(const LAS bf16x8*)(lds + bbase[b][h] + n * 2048 + k * 1024); } while (0)
; #define PG8_WAIT_V(n) asm volatile("s_waitcnt vmcnt(" #n ")" ::: "memory")
; #define PG8_WAIT_L(n) asm volatile("s_waitcnt lgkmcnt(" #n ")" ::: "memory")
; #define PG8_BAR __builtin_amdgcn_s_barrier()
; #define PG8_SCHED __builtin_amdgcn_sched_barrier(0)
; template <class Epi>
; __device__ __forceinline__ void gemm_phase(LAS unsigned char* lds, const Gemm g, const StaticOrder& S, const Epi& E) {
;     ...
;             PG8_WAIT_V(8); PG8_WAIT_L(0); PG8_BAR; PG8_MMA2B(0, At, At2, B0); PG8_BAR; PG8_SCHED;
;             PG8_LDB(B0, 1, 1); PG8_STAGE(PG8_SB(1, 0), b3, voffB); PG8_STAGE(PG8_SA(1, 0), a3, voffA); PG8_STAGE(PG8_SA(1, 1), a3 + hstepA, voffA);
;             PG8_WAIT_V(8); PG8_WAIT_L(0); PG8_BAR; PG8_MMA2B(1, At, At2, B0); PG8_BAR; PG8_SCHED;
;         }
;         if (wr == 0) PG8_BAR;
;     __device__ __forceinline__ void operator()(f32x4 (&acc)[2][2][4][2], const Unit& u, int wr, int wc, int fr, int fq) const {
;     ...
;         { const int t = (wc * 4 + fq) * 16 + fr;
;           if (wr == 0) { const float* sp = ssq + ((size_t)u.pm * 256 + t) * 16; const f32x4 a = *(const f32x4*)sp, b = *(const f32x4*)(sp + 4), c = *(const f32x4*)(sp + 8), d = *(const f32x4*)(sp + 12);
.Lh0skip_14:
	s_barrier
	s_waitcnt lgkmcnt(14)
	v_mfma_f32_16x16x32_bf16 v[80:83], v[68:71], v[132:135], v[80:83]
	v_mfma_f32_16x16x32_bf16 v[76:79], v[88:91], v[132:135], v[76:79]
	s_waitcnt lgkmcnt(13)
	v_mfma_f32_16x16x32_bf16 v[148:151], v[68:71], v[152:155], v[148:151]
	v_mfma_f32_16x16x32_bf16 v[52:55], v[88:91], v[152:155], v[52:55]
	s_waitcnt lgkmcnt(11)
	v_mfma_f32_16x16x32_bf16 v[144:147], v[68:71], v[166:169], v[144:147]
	v_mfma_f32_16x16x32_bf16 v[48:51], v[88:91], v[166:169], v[48:51]
	s_waitcnt lgkmcnt(9)
	v_mfma_f32_16x16x32_bf16 v[136:139], v[68:71], v[182:185], v[136:139]
	v_mfma_f32_16x16x32_bf16 v[40:43], v[88:91], v[182:185], v[40:43]
	s_waitcnt lgkmcnt(7)
	v_mfma_f32_16x16x32_bf16 v[124:127], v[68:71], v[190:193], v[124:127]
	v_mfma_f32_16x16x32_bf16 v[28:31], v[88:91], v[190:193], v[28:31]
	s_waitcnt lgkmcnt(5)
	v_mfma_f32_16x16x32_bf16 v[120:123], v[68:71], v[198:201], v[120:123]
	v_mfma_f32_16x16x32_bf16 v[24:27], v[88:91], v[198:201], v[24:27]
	s_waitcnt lgkmcnt(3)
	v_mfma_f32_16x16x32_bf16 v[112:115], v[68:71], v[226:229], v[112:115]
	v_mfma_f32_16x16x32_bf16 v[16:19], v[88:91], v[226:229], v[16:19]
	s_waitcnt lgkmcnt(1)
	v_mfma_f32_16x16x32_bf16 v[64:67], v[68:71], v[234:237], v[64:67]
	v_mfma_f32_16x16x32_bf16 v[4:7], v[88:91], v[234:237], v[4:7]
	v_mfma_f32_16x16x32_bf16 v[80:83], v[84:87], v[140:143], v[80:83]
	v_mfma_f32_16x16x32_bf16 v[76:79], v[92:95], v[140:143], v[76:79]
	v_mfma_f32_16x16x32_bf16 v[148:151], v[84:87], v[156:159], v[148:151]
	v_mfma_f32_16x16x32_bf16 v[52:55], v[92:95], v[156:159], v[52:55]
	v_mfma_f32_16x16x32_bf16 v[144:147], v[84:87], v[178:181], v[144:147]
	v_mfma_f32_16x16x32_bf16 v[48:51], v[92:95], v[178:181], v[48:51]
	v_mfma_f32_16x16x32_bf16 v[136:139], v[84:87], v[186:189], v[136:139]
	v_mfma_f32_16x16x32_bf16 v[40:43], v[92:95], v[186:189], v[40:43]
	v_mfma_f32_16x16x32_bf16 v[124:127], v[84:87], v[194:197], v[124:127]
	v_mfma_f32_16x16x32_bf16 v[28:31], v[92:95], v[194:197], v[28:31]
	v_mfma_f32_16x16x32_bf16 v[120:123], v[84:87], v[202:205], v[120:123]
	v_mfma_f32_16x16x32_bf16 v[24:27], v[92:95], v[202:205], v[24:27]
	v_mfma_f32_16x16x32_bf16 v[112:115], v[84:87], v[230:233], v[112:115]
	v_mfma_f32_16x16x32_bf16 v[16:19], v[92:95], v[230:233], v[16:19]
	s_waitcnt lgkmcnt(0)
	v_mfma_f32_16x16x32_bf16 v[64:67], v[84:87], v[238:241], v[64:67]
	v_mfma_f32_16x16x32_bf16 v[4:7], v[92:95], v[238:241], v[4:7]
	s_barrier
	s_add_u32 s10, s84, 0x80
	ds_read_b128 v[68:71], v224
	ds_read_b128 v[84:87], v224 offset:1024
	ds_read_b128 v[88:91], v224 offset:2048
	ds_read_b128 v[92:95], v224 offset:3072
	s_addc_u32 s11, s85, 0
	s_mov_b32 m0, s88
	s_nop 0
	global_load_lds_dwordx4 v217, s[10:11]
	s_mov_b32 m0, s89
	s_nop 0
	global_load_lds_dwordx4 v219, s[10:11]
	s_mov_b32 m0, s95
	s_nop 0
	global_load_lds_dwordx4 v216, s[16:17]
	s_mov_b32 m0, s37
	s_nop 0
	global_load_lds_dwordx4 v218, s[16:17]
	s_add_u32 s10, s14, 0x40080
	s_addc_u32 s11, s15, 0
	s_mov_b32 m0, s56
	s_nop 0
	global_load_lds_dwordx4 v216, s[10:11]
	s_mov_b32 m0, s57
	s_nop 0
	global_load_lds_dwordx4 v218, s[10:11]
	s_waitcnt vmcnt(8)
	s_cmp_lg_u64 s[90:91], 0
	s_cbranch_scc1 .Lh0skip_15
	s_waitcnt lgkmcnt(0)
.Lh0skip_15:
	s_barrier
	s_waitcnt lgkmcnt(3)
	v_mfma_f32_16x16x32_bf16 v[72:75], v[68:71], v[132:135], v[72:75]
	s_waitcnt lgkmcnt(1)
	v_mfma_f32_16x16x32_bf16 v[56:59], v[88:91], v[132:135], v[56:59]
	v_mfma_f32_16x16x32_bf16 v[96:99], v[68:71], v[152:155], v[96:99]
	v_mfma_f32_16x16x32_bf16 v[72:75], v[84:87], v[140:143], v[72:75]
	s_waitcnt lgkmcnt(0)
	v_mfma_f32_16x16x32_bf16 v[56:59], v[92:95], v[140:143], v[56:59]
	v_mfma_f32_16x16x32_bf16 v[140:143], v[84:87], v[156:159], v[96:99]
	v_mfma_f32_16x16x32_bf16 v[96:99], v[68:71], v[166:169], v[100:103]
	v_mfma_f32_16x16x32_bf16 v[132:135], v[84:87], v[178:181], v[96:99]
	v_mfma_f32_16x16x32_bf16 v[96:99], v[68:71], v[182:185], v[128:131]
	v_mfma_f32_16x16x32_bf16 v[128:131], v[84:87], v[186:189], v[96:99]
	v_mfma_f32_16x16x32_bf16 v[96:99], v[68:71], v[190:193], v[116:119]
	v_mfma_f32_16x16x32_bf16 v[116:119], v[84:87], v[194:197], v[96:99]
	v_mfma_f32_16x16x32_bf16 v[96:99], v[68:71], v[198:201], v[108:111]
	v_mfma_f32_16x16x32_bf16 v[44:47], v[88:91], v[152:155], v[44:47]
	v_mfma_f32_16x16x32_bf16 v[36:39], v[88:91], v[166:169], v[36:39]
	v_mfma_f32_16x16x32_bf16 v[32:35], v[88:91], v[182:185], v[32:35]
	v_mfma_f32_16x16x32_bf16 v[20:23], v[88:91], v[190:193], v[20:23]
	v_mfma_f32_16x16x32_bf16 v[108:111], v[84:87], v[202:205], v[96:99]
	v_mfma_f32_16x16x32_bf16 v[12:15], v[88:91], v[198:201], v[12:15]
	v_mfma_f32_16x16x32_bf16 v[96:99], v[68:71], v[226:229], v[104:107]
	v_mfma_f32_16x16x32_bf16 v[8:11], v[88:91], v[226:229], v[8:11]
	v_mfma_f32_16x16x32_bf16 v[60:63], v[68:71], v[234:237], v[60:63]
	v_mfma_f32_16x16x32_bf16 v[0:3], v[88:91], v[234:237], v[0:3]
	v_mfma_f32_16x16x32_bf16 v[44:47], v[92:95], v[156:159], v[44:47]
	v_mfma_f32_16x16x32_bf16 v[36:39], v[92:95], v[178:181], v[36:39]
	v_mfma_f32_16x16x32_bf16 v[32:35], v[92:95], v[186:189], v[32:35]
	v_mfma_f32_16x16x32_bf16 v[20:23], v[92:95], v[194:197], v[20:23]
	v_mfma_f32_16x16x32_bf16 v[12:15], v[92:95], v[202:205], v[12:15]
	v_mfma_f32_16x16x32_bf16 v[104:107], v[84:87], v[230:233], v[96:99]
	v_mfma_f32_16x16x32_bf16 v[8:11], v[92:95], v[230:233], v[8:11]
	v_mfma_f32_16x16x32_bf16 v[60:63], v[84:87], v[238:241], v[60:63]
	v_mfma_f32_16x16x32_bf16 v[0:3], v[92:95], v[238:241], v[0:3]
	s_barrier
	s_add_i32 s69, s69, 2
	s_add_u32 vcc_hi, vcc_hi, 0x100
	s_addc_u32 s68, s68, 0
	s_cmp_gt_u32 s69, 13
	s_mov_b64 s[10:11], s[12:13]
	s_cbranch_scc0 .LBB0_1027
	s_and_b64 vcc, exec, s[90:91]
	s_cbranch_vccz .LBB0_1030
	v_lshlrev_b32_e32 v68, 4, v215
	v_add3_u32 v68, v214, s59, v68
	s_ashr_i32 s97, s96, 31
	s_lshl_b64 s[12:13], s[96:97], 14
	v_ashrrev_i32_e32 v69, 31, v68
	s_add_u32 s12, s18, s12
	s_addc_u32 s13, s19, s13
	v_lshlrev_b64 v[70:71], 6, v[68:69]
	v_lshl_add_u64 v[70:71], s[12:13], 0, v[70:71]
	global_load_dwordx4 v[86:89], v[70:71], off
	global_load_dwordx4 v[90:93], v[70:71], off offset:16
	global_load_dwordx4 v[94:97], v[70:71], off offset:32
	global_load_dwordx4 v[98:101], v[70:71], off offset:48
	s_barrier

; #define PG8_STAGE(bufoff, gbase, voff) do { _Pragma("unroll") for (int _i = 0; _i < 2; ++_i) { \
;         const unsigned _m0 = ldsu + (unsigned)(bufoff) + ldsw + (unsigned)(_i * 8192); \
;         asm volatile("s_mov_b32 m0, %2\n\ts_nop 0\n\tglobal_load_lds_dwordx4 %0, %1" :: "v"((voff)[_i]), "s"((const char*)(gbase)), "s"(_m0) : "memory"); } } while (0)
; #define PG8_LDA(dst, b, h) do { _Pragma("unroll") for (int m = 0; m < 4; ++m) _Pragma("unroll") for (int k = 0; k < 2; ++k) dst[m][k] = *(const LAS bf16x8*)(lds + PG8_SA(b, h) + aoff + m * 2048 + k * 1024); } while (0)
; #define PG8_LDB(dst, b, h) do { _Pragma("unroll") for (int n = 0; n < 2; ++n) _Pragma("unroll") for (int k = 0; k < 2; ++k) dst[n][k] = *(const LAS bf16x8*)(lds + bbase[b][h] + n * 2048 + k * 1024); } while (0)
; #define PG8_WAIT_V(n) asm volatile("s_waitcnt vmcnt(" #n ")" ::: "memory")
; #define PG8_WAIT_L(n) asm volatile("s_waitcnt lgkmcnt(" #n ")" ::: "memory")
; #define PG8_BAR __builtin_amdgcn_s_barrier()
; #define PG8_SCHED __builtin_amdgcn_sched_barrier(0)
; template <class Epi>
; __device__ __forceinline__ void gemm_phase(LAS unsigned char* lds, const Gemm g, const StaticOrder& S, const Epi& E) {
;     ...
;             const bool last = (t == nt - 2);
;             const char* a2 = last ? nA : cA + (size_t)(t + 2) * kstep; const char* b2 = last ? nB : cB + (size_t)(t + 2) * kstep;
;             const char* a3 = a2 + kstep; const char* b3 = b2 + kstep;
;             const char* b1 = cB + (size_t)(t + 1) * kstep;
;             PG8_LDB(B0, 0, 0); PG8_SCHED; PG8_LDA(At, 0, 0); PG8_LDA(At2, 0, 1); PG8_STAGE(PG8_SB(1, 1), b1 + hstepB, voffB);
;             PG8_WAIT_V(8); PG8_WAIT_L(0); PG8_BAR; PG8_MMA2B(0, At, At2, B0); PG8_BAR; PG8_SCHED;
;             PG8_LDB(B0, 0, 1); PG8_STAGE(PG8_SB(0, 0), b2, voffB); PG8_STAGE(PG8_SA(0, 0), a2, voffA); PG8_STAGE(PG8_SA(0, 1), a2 + hstepA, voffA);
;             PG8_WAIT_V(8); PG8_WAIT_L(0); PG8_BAR; PG8_MMA2B(1, At, At2, B0); PG8_BAR; PG8_SCHED;
.LBB0_1140:
	ds_read_b128 v[128:131], v138
	ds_read_b128 v[144:147], v138 offset:1024
	ds_read_b128 v[148:151], v138 offset:2048
	ds_read_b128 v[152:155], v138 offset:3072
	s_cmp_eq_u32 s68, 40
	s_cselect_b32 s14, s4, s80
	s_cselect_b32 s15, s5, s81
	s_cselect_b32 s42, s10, s82
	s_cselect_b32 s43, s11, s83
	s_add_u32 s16, s14, 0x80
	s_addc_u32 s17, s15, 0
	s_add_u32 s38, s42, 0x80
	s_addc_u32 s39, s43, 0
	ds_read_b128 v[156:159], v139
	ds_read_b128 v[166:169], v139 offset:1024
	ds_read_b128 v[178:181], v139 offset:2048
	ds_read_b128 v[182:185], v139 offset:3072
	ds_read_b128 v[186:189], v139 offset:4096
	ds_read_b128 v[190:193], v139 offset:5120
	ds_read_b128 v[194:197], v139 offset:6144
	ds_read_b128 v[198:201], v139 offset:7168
	ds_read_b128 v[202:205], v139 offset:16384
	ds_read_b128 v[214:217], v139 offset:17408
	ds_read_b128 v[218:221], v139 offset:18432
	ds_read_b128 v[222:225], v139 offset:19456
	ds_read_b128 v[226:229], v139 offset:20480
	ds_read_b128 v[230:233], v139 offset:21504
	ds_read_b128 v[234:237], v139 offset:22528
	ds_read_b128 v[238:241], v139 offset:23552
	s_mov_b32 m0, s61
	s_nop 0
	global_load_lds_dwordx4 v133, s[12:13]
	s_mov_b32 m0, s63
	s_nop 0
	global_load_lds_dwordx4 v135, s[12:13]
	s_waitcnt vmcnt(8)
	s_cmp_lg_u64 s[2:3], 0
	s_cbranch_scc1 .Lh0skip_16
	s_waitcnt lgkmcnt(0)
.Lh0skip_16:
	s_barrier
	s_waitcnt lgkmcnt(14)
	v_mfma_f32_16x16x32_bf16 v[124:127], v[128:131], v[156:159], v[124:127]
	v_mfma_f32_16x16x32_bf16 v[120:123], v[148:151], v[156:159], v[120:123]
	s_waitcnt lgkmcnt(13)
	v_mfma_f32_16x16x32_bf16 v[108:111], v[128:131], v[178:181], v[108:111]
	v_mfma_f32_16x16x32_bf16 v[104:107], v[148:151], v[178:181], v[104:107]
	s_waitcnt lgkmcnt(11)
	v_mfma_f32_16x16x32_bf16 v[92:95], v[128:131], v[186:189], v[92:95]
	v_mfma_f32_16x16x32_bf16 v[88:91], v[148:151], v[186:189], v[88:91]
	s_waitcnt lgkmcnt(9)
	v_mfma_f32_16x16x32_bf16 v[76:79], v[128:131], v[194:197], v[76:79]
	v_mfma_f32_16x16x32_bf16 v[72:75], v[148:151], v[194:197], v[72:75]
	s_waitcnt lgkmcnt(7)
	v_mfma_f32_16x16x32_bf16 v[60:63], v[128:131], v[202:205], v[60:63]
	v_mfma_f32_16x16x32_bf16 v[56:59], v[148:151], v[202:205], v[56:59]
	s_waitcnt lgkmcnt(5)
	v_mfma_f32_16x16x32_bf16 v[44:47], v[128:131], v[218:221], v[44:47]
	v_mfma_f32_16x16x32_bf16 v[40:43], v[148:151], v[218:221], v[40:43]
	s_waitcnt lgkmcnt(3)
	v_mfma_f32_16x16x32_bf16 v[28:31], v[128:131], v[226:229], v[28:31]
	v_mfma_f32_16x16x32_bf16 v[24:27], v[148:151], v[226:229], v[24:27]
	s_waitcnt lgkmcnt(1)
	v_mfma_f32_16x16x32_bf16 v[12:15], v[128:131], v[234:237], v[12:15]
	v_mfma_f32_16x16x32_bf16 v[8:11], v[148:151], v[234:237], v[8:11]
	v_mfma_f32_16x16x32_bf16 v[124:127], v[144:147], v[166:169], v[124:127]
	v_mfma_f32_16x16x32_bf16 v[120:123], v[152:155], v[166:169], v[120:123]
	v_mfma_f32_16x16x32_bf16 v[108:111], v[144:147], v[182:185], v[108:111]
	v_mfma_f32_16x16x32_bf16 v[104:107], v[152:155], v[182:185], v[104:107]
	v_mfma_f32_16x16x32_bf16 v[92:95], v[144:147], v[190:193], v[92:95]
	v_mfma_f32_16x16x32_bf16 v[88:91], v[152:155], v[190:193], v[88:91]
	v_mfma_f32_16x16x32_bf16 v[76:79], v[144:147], v[198:201], v[76:79]
	v_mfma_f32_16x16x32_bf16 v[72:75], v[152:155], v[198:201], v[72:75]
	v_mfma_f32_16x16x32_bf16 v[60:63], v[144:147], v[214:217], v[60:63]
	v_mfma_f32_16x16x32_bf16 v[56:59], v[152:155], v[214:217], v[56:59]
	v_mfma_f32_16x16x32_bf16 v[44:47], v[144:147], v[222:225], v[44:47]
	v_mfma_f32_16x16x32_bf16 v[40:43], v[152:155], v[222:225], v[40:43]
	v_mfma_f32_16x16x32_bf16 v[28:31], v[144:147], v[230:233], v[28:31]
	v_mfma_f32_16x16x32_bf16 v[24:27], v[152:155], v[230:233], v[24:27]
	s_waitcnt lgkmcnt(0)
	v_mfma_f32_16x16x32_bf16 v[12:15], v[144:147], v[238:241], v[12:15]
	v_mfma_f32_16x16x32_bf16 v[8:11], v[152:155], v[238:241], v[8:11]
	s_barrier
	ds_read_b128 v[128:131], v140
	ds_read_b128 v[144:147], v140 offset:1024
	ds_read_b128 v[148:151], v140 offset:2048
	ds_read_b128 v[152:155], v140 offset:3072
	s_mov_b32 m0, s48
	s_nop 0
	global_load_lds_dwordx4 v133, s[42:43]
	s_mov_b32 m0, s49
	s_nop 0
	global_load_lds_dwordx4 v135, s[42:43]
	s_mov_b32 m0, s47
	s_nop 0
	global_load_lds_dwordx4 v132, s[14:15]
	s_mov_b32 m0, s50
	s_nop 0
	global_load_lds_dwordx4 v134, s[14:15]
	s_add_u32 s84, s14, 0xb0000
	s_addc_u32 s85, s15, 0
	s_mov_b32 m0, s51
	s_nop 0
	global_load_lds_dwordx4 v132, s[84:85]
	s_mov_b32 m0, s52
	s_nop 0
	global_load_lds_dwordx4 v134, s[84:85]
	s_waitcnt vmcnt(8)
	s_cmp_lg_u64 s[2:3], 0
	s_cbranch_scc1 .Lh0skip_17
	s_waitcnt lgkmcnt(0)
; #define PG8_STAGE(bufoff, gbase, voff) do { _Pragma("unroll") for (int _i = 0; _i < 2; ++_i) { \
;         const unsigned _m0 = ldsu + (unsigned)(bufoff) + ldsw + (unsigned)(_i * 8192); \
;         asm volatile("s_mov_b32 m0, %2\n\ts_nop 0\n\tglobal_load_lds_dwordx4 %0, %1" :: "v"((voff)[_i]), "s"((const char*)(gbase)), "s"(_m0) : "memory"); } } while (0)
; #define PG8_LDA(dst, b, h) do { _Pragma("unroll") for (int m = 0; m < 4; ++m) _Pragma("unroll") for (int k = 0; k < 2; ++k) dst[m][k] = *(const LAS bf16x8*)(lds + PG8_SA(b, h) + aoff + m * 2048 + k * 1024); } while (0)
; #define PG8_LDB(dst, b, h) do { _Pragma("unroll") for (int n = 0; n < 2; ++n) _Pragma("unroll") for (int k = 0; k < 2; ++k) dst[n][k] = *(const LAS bf16x8*)(lds + bbase[b][h] + n * 2048 + k * 1024); } while (0)
; #define PG8_WAIT_V(n) asm volatile("s_waitcnt vmcnt(" #n ")" ::: "memory")
; #define PG8_WAIT_L(n) asm volatile("s_waitcnt lgkmcnt(" #n ")" ::: "memory")
; #define PG8_BAR __builtin_amdgcn_s_barrier()
; #define PG8_SCHED __builtin_amdgcn_sched_barrier(0)
; template <class Epi>
; __device__ __forceinline__ void gemm_phase(LAS unsigned char* lds, const Gemm g, const StaticOrder& S, const Epi& E) {
;     ...
;             PG8_WAIT_V(8); PG8_WAIT_L(0); PG8_BAR; PG8_MMA2B(1, At, At2, B0); PG8_BAR; PG8_SCHED;
;             PG8_LDB(B0, 1, 0); PG8_SCHED; PG8_LDA(At, 1, 0); PG8_LDA(At2, 1, 1); PG8_STAGE(PG8_SB(0, 1), b2 + hstepB, voffB);
;             PG8_WAIT_V(8); PG8_WAIT_L(0); PG8_BAR; PG8_MMA2B(0, At, At2, B0); PG8_BAR; PG8_SCHED;
.Lh0skip_17:
	s_barrier
	s_waitcnt lgkmcnt(3)
	v_mfma_f32_16x16x32_bf16 v[116:119], v[128:131], v[156:159], v[116:119]
	s_waitcnt lgkmcnt(1)
	v_mfma_f32_16x16x32_bf16 v[112:115], v[148:151], v[156:159], v[112:115]
	v_mfma_f32_16x16x32_bf16 v[100:103], v[128:131], v[178:181], v[100:103]
	v_mfma_f32_16x16x32_bf16 v[96:99], v[148:151], v[178:181], v[96:99]
	v_mfma_f32_16x16x32_bf16 v[84:87], v[128:131], v[186:189], v[84:87]
	v_mfma_f32_16x16x32_bf16 v[80:83], v[148:151], v[186:189], v[80:83]
	v_mfma_f32_16x16x32_bf16 v[68:71], v[128:131], v[194:197], v[68:71]
	v_mfma_f32_16x16x32_bf16 v[64:67], v[148:151], v[194:197], v[64:67]
	v_mfma_f32_16x16x32_bf16 v[52:55], v[128:131], v[202:205], v[52:55]
	v_mfma_f32_16x16x32_bf16 v[48:51], v[148:151], v[202:205], v[48:51]
	v_mfma_f32_16x16x32_bf16 v[36:39], v[128:131], v[218:221], v[36:39]
	v_mfma_f32_16x16x32_bf16 v[32:35], v[148:151], v[218:221], v[32:35]
	v_mfma_f32_16x16x32_bf16 v[20:23], v[128:131], v[226:229], v[20:23]
	v_mfma_f32_16x16x32_bf16 v[16:19], v[148:151], v[226:229], v[16:19]
	v_mfma_f32_16x16x32_bf16 v[4:7], v[128:131], v[234:237], v[4:7]
	v_mfma_f32_16x16x32_bf16 v[0:3], v[148:151], v[234:237], v[0:3]
	v_mfma_f32_16x16x32_bf16 v[116:119], v[144:147], v[166:169], v[116:119]
	s_waitcnt lgkmcnt(0)
	v_mfma_f32_16x16x32_bf16 v[112:115], v[152:155], v[166:169], v[112:115]
	v_mfma_f32_16x16x32_bf16 v[100:103], v[144:147], v[182:185], v[100:103]
	v_mfma_f32_16x16x32_bf16 v[96:99], v[152:155], v[182:185], v[96:99]
	v_mfma_f32_16x16x32_bf16 v[84:87], v[144:147], v[190:193], v[84:87]
	v_mfma_f32_16x16x32_bf16 v[80:83], v[152:155], v[190:193], v[80:83]
	v_mfma_f32_16x16x32_bf16 v[68:71], v[144:147], v[198:201], v[68:71]
	v_mfma_f32_16x16x32_bf16 v[64:67], v[152:155], v[198:201], v[64:67]
	v_mfma_f32_16x16x32_bf16 v[52:55], v[144:147], v[214:217], v[52:55]
	v_mfma_f32_16x16x32_bf16 v[48:51], v[152:155], v[214:217], v[48:51]
	v_mfma_f32_16x16x32_bf16 v[36:39], v[144:147], v[222:225], v[36:39]
	v_mfma_f32_16x16x32_bf16 v[32:35], v[152:155], v[222:225], v[32:35]
	v_mfma_f32_16x16x32_bf16 v[20:23], v[144:147], v[230:233], v[20:23]
	v_mfma_f32_16x16x32_bf16 v[16:19], v[152:155], v[230:233], v[16:19]
	v_mfma_f32_16x16x32_bf16 v[4:7], v[144:147], v[238:241], v[4:7]
	v_mfma_f32_16x16x32_bf16 v[0:3], v[152:155], v[238:241], v[0:3]
	s_barrier
	ds_read_b128 v[128:131], v141
	ds_read_b128 v[144:147], v141 offset:1024
	ds_read_b128 v[148:151], v141 offset:2048
	ds_read_b128 v[152:155], v141 offset:3072
	ds_read_b128 v[156:159], v139 offset:32768
	ds_read_b128 v[166:169], v139 offset:33792
	ds_read_b128 v[178:181], v139 offset:34816
	ds_read_b128 v[182:185], v139 offset:35840
	ds_read_b128 v[186:189], v139 offset:36864
	ds_read_b128 v[190:193], v139 offset:37888
	ds_read_b128 v[194:197], v139 offset:38912
	ds_read_b128 v[198:201], v139 offset:39936
	ds_read_b128 v[202:205], v139 offset:49152
	ds_read_b128 v[214:217], v139 offset:50176
	ds_read_b128 v[218:221], v139 offset:51200
	ds_read_b128 v[222:225], v139 offset:52224
	ds_read_b128 v[226:229], v139 offset:53248
	ds_read_b128 v[230:233], v139 offset:54272
	ds_read_b128 v[234:237], v139 offset:55296
	ds_read_b128 v[238:241], v139 offset:56320
	s_add_u32 s42, s42, 0xb0000
	s_addc_u32 s43, s43, 0
	s_mov_b32 m0, s53
	s_nop 0
	global_load_lds_dwordx4 v133, s[42:43]
	s_mov_b32 m0, s54
	s_nop 0
	global_load_lds_dwordx4 v135, s[42:43]
	s_waitcnt vmcnt(8)
	s_cmp_lg_u64 s[2:3], 0
	s_cbranch_scc1 .Lh0skip_18
	s_waitcnt lgkmcnt(0)
; #define PG8_STAGE(bufoff, gbase, voff) do { _Pragma("unroll") for (int _i = 0; _i < 2; ++_i) { \
;         const unsigned _m0 = ldsu + (unsigned)(bufoff) + ldsw + (unsigned)(_i * 8192); \
;         asm volatile("s_mov_b32 m0, %2\n\ts_nop 0\n\tglobal_load_lds_dwordx4 %0, %1" :: "v"((voff)[_i]), "s"((const char*)(gbase)), "s"(_m0) : "memory"); } } while (0)
; #define PG8_LDB(dst, b, h) do { _Pragma("unroll") for (int n = 0; n < 2; ++n) _Pragma("unroll") for (int k = 0; k < 2; ++k) dst[n][k] = *(const LAS bf16x8*)(lds + bbase[b][h] + n * 2048 + k * 1024); } while (0)
; #define PG8_WAIT_V(n) asm volatile("s_waitcnt vmcnt(" #n ")" ::: "memory")
; #define PG8_WAIT_L(n) asm volatile("s_waitcnt lgkmcnt(" #n ")" ::: "memory")
; #define PG8_BAR __builtin_amdgcn_s_barrier()
; #define PG8_SCHED __builtin_amdgcn_sched_barrier(0)
; template <class Epi>
; __device__ __forceinline__ void gemm_phase(LAS unsigned char* lds, const Gemm g, const StaticOrder& S, const Epi& E) {
;     ...
;             PG8_WAIT_V(8); PG8_WAIT_L(0); PG8_BAR; PG8_MMA2B(0, At, At2, B0); PG8_BAR; PG8_SCHED;
;             PG8_LDB(B0, 1, 1); PG8_STAGE(PG8_SB(1, 0), b3, voffB); PG8_STAGE(PG8_SA(1, 0), a3, voffA); PG8_STAGE(PG8_SA(1, 1), a3 + hstepA, voffA);
;             PG8_WAIT_V(8); PG8_WAIT_L(0); PG8_BAR; PG8_MMA2B(1, At, At2, B0); PG8_BAR; PG8_SCHED;
;         }
;         if (wr == 0) PG8_BAR;
.Lh0skip_18:
	s_barrier
	s_waitcnt lgkmcnt(14)
	v_mfma_f32_16x16x32_bf16 v[124:127], v[128:131], v[156:159], v[124:127]
	v_mfma_f32_16x16x32_bf16 v[120:123], v[148:151], v[156:159], v[120:123]
	s_waitcnt lgkmcnt(13)
	v_mfma_f32_16x16x32_bf16 v[108:111], v[128:131], v[178:181], v[108:111]
	v_mfma_f32_16x16x32_bf16 v[104:107], v[148:151], v[178:181], v[104:107]
	s_waitcnt lgkmcnt(11)
	v_mfma_f32_16x16x32_bf16 v[92:95], v[128:131], v[186:189], v[92:95]
	v_mfma_f32_16x16x32_bf16 v[88:91], v[148:151], v[186:189], v[88:91]
	s_waitcnt lgkmcnt(9)
	v_mfma_f32_16x16x32_bf16 v[76:79], v[128:131], v[194:197], v[76:79]
	v_mfma_f32_16x16x32_bf16 v[72:75], v[148:151], v[194:197], v[72:75]
	s_waitcnt lgkmcnt(7)
	v_mfma_f32_16x16x32_bf16 v[60:63], v[128:131], v[202:205], v[60:63]
	v_mfma_f32_16x16x32_bf16 v[56:59], v[148:151], v[202:205], v[56:59]
	s_waitcnt lgkmcnt(5)
	v_mfma_f32_16x16x32_bf16 v[44:47], v[128:131], v[218:221], v[44:47]
	v_mfma_f32_16x16x32_bf16 v[40:43], v[148:151], v[218:221], v[40:43]
	s_waitcnt lgkmcnt(3)
	v_mfma_f32_16x16x32_bf16 v[28:31], v[128:131], v[226:229], v[28:31]
	v_mfma_f32_16x16x32_bf16 v[24:27], v[148:151], v[226:229], v[24:27]
	s_waitcnt lgkmcnt(1)
	v_mfma_f32_16x16x32_bf16 v[12:15], v[128:131], v[234:237], v[12:15]
	v_mfma_f32_16x16x32_bf16 v[8:11], v[148:151], v[234:237], v[8:11]
	v_mfma_f32_16x16x32_bf16 v[124:127], v[144:147], v[166:169], v[124:127]
	v_mfma_f32_16x16x32_bf16 v[120:123], v[152:155], v[166:169], v[120:123]
	v_mfma_f32_16x16x32_bf16 v[108:111], v[144:147], v[182:185], v[108:111]
	v_mfma_f32_16x16x32_bf16 v[104:107], v[152:155], v[182:185], v[104:107]
	v_mfma_f32_16x16x32_bf16 v[92:95], v[144:147], v[190:193], v[92:95]
	v_mfma_f32_16x16x32_bf16 v[88:91], v[152:155], v[190:193], v[88:91]
	v_mfma_f32_16x16x32_bf16 v[76:79], v[144:147], v[198:201], v[76:79]
	v_mfma_f32_16x16x32_bf16 v[72:75], v[152:155], v[198:201], v[72:75]
	v_mfma_f32_16x16x32_bf16 v[60:63], v[144:147], v[214:217], v[60:63]
	v_mfma_f32_16x16x32_bf16 v[56:59], v[152:155], v[214:217], v[56:59]
	v_mfma_f32_16x16x32_bf16 v[44:47], v[144:147], v[222:225], v[44:47]
	v_mfma_f32_16x16x32_bf16 v[40:43], v[152:155], v[222:225], v[40:43]
	v_mfma_f32_16x16x32_bf16 v[28:31], v[144:147], v[230:233], v[28:31]
	v_mfma_f32_16x16x32_bf16 v[24:27], v[152:155], v[230:233], v[24:27]
	s_waitcnt lgkmcnt(0)
	v_mfma_f32_16x16x32_bf16 v[12:15], v[144:147], v[238:241], v[12:15]
	v_mfma_f32_16x16x32_bf16 v[8:11], v[152:155], v[238:241], v[8:11]
	s_barrier
	ds_read_b128 v[128:131], v142
	ds_read_b128 v[144:147], v142 offset:1024
	ds_read_b128 v[148:151], v142 offset:2048
	ds_read_b128 v[152:155], v142 offset:3072
	s_mov_b32 m0, s55
	s_nop 0
	global_load_lds_dwordx4 v133, s[38:39]
	s_mov_b32 m0, s56
	s_nop 0
	global_load_lds_dwordx4 v135, s[38:39]
	s_mov_b32 m0, s57
	s_nop 0
	global_load_lds_dwordx4 v132, s[16:17]
	s_mov_b32 m0, s58
	s_nop 0
	global_load_lds_dwordx4 v134, s[16:17]
	s_add_u32 s14, s14, 0xb0080
	s_addc_u32 s15, s15, 0
	s_mov_b32 m0, s59
	s_nop 0
	global_load_lds_dwordx4 v132, s[14:15]
	s_mov_b32 m0, s60
	s_nop 0
	global_load_lds_dwordx4 v134, s[14:15]
	s_waitcnt vmcnt(8)
	s_cmp_lg_u64 s[2:3], 0
	s_cbranch_scc1 .Lh0skip_19
	s_waitcnt lgkmcnt(0)
.Lh0skip_19:
	s_barrier
	s_waitcnt lgkmcnt(3)
	v_mfma_f32_16x16x32_bf16 v[116:119], v[128:131], v[156:159], v[116:119]
	s_waitcnt lgkmcnt(1)
	v_mfma_f32_16x16x32_bf16 v[112:115], v[148:151], v[156:159], v[112:115]
	v_mfma_f32_16x16x32_bf16 v[100:103], v[128:131], v[178:181], v[100:103]
	v_mfma_f32_16x16x32_bf16 v[96:99], v[148:151], v[178:181], v[96:99]
	v_mfma_f32_16x16x32_bf16 v[84:87], v[128:131], v[186:189], v[84:87]
	v_mfma_f32_16x16x32_bf16 v[80:83], v[148:151], v[186:189], v[80:83]
	v_mfma_f32_16x16x32_bf16 v[68:71], v[128:131], v[194:197], v[68:71]
	v_mfma_f32_16x16x32_bf16 v[64:67], v[148:151], v[194:197], v[64:67]
	v_mfma_f32_16x16x32_bf16 v[52:55], v[128:131], v[202:205], v[52:55]
	v_mfma_f32_16x16x32_bf16 v[48:51], v[148:151], v[202:205], v[48:51]
	v_mfma_f32_16x16x32_bf16 v[36:39], v[128:131], v[218:221], v[36:39]
	v_mfma_f32_16x16x32_bf16 v[32:35], v[148:151], v[218:221], v[32:35]
	v_mfma_f32_16x16x32_bf16 v[20:23], v[128:131], v[226:229], v[20:23]
	v_mfma_f32_16x16x32_bf16 v[16:19], v[148:151], v[226:229], v[16:19]
	v_mfma_f32_16x16x32_bf16 v[4:7], v[128:131], v[234:237], v[4:7]
	v_mfma_f32_16x16x32_bf16 v[0:3], v[148:151], v[234:237], v[0:3]
	v_mfma_f32_16x16x32_bf16 v[116:119], v[144:147], v[166:169], v[116:119]
	s_waitcnt lgkmcnt(0)
	v_mfma_f32_16x16x32_bf16 v[112:115], v[152:155], v[166:169], v[112:115]
	v_mfma_f32_16x16x32_bf16 v[100:103], v[144:147], v[182:185], v[100:103]
	v_mfma_f32_16x16x32_bf16 v[96:99], v[152:155], v[182:185], v[96:99]
	v_mfma_f32_16x16x32_bf16 v[84:87], v[144:147], v[190:193], v[84:87]
	v_mfma_f32_16x16x32_bf16 v[80:83], v[152:155], v[190:193], v[80:83]
	v_mfma_f32_16x16x32_bf16 v[68:71], v[144:147], v[198:201], v[68:71]
	v_mfma_f32_16x16x32_bf16 v[64:67], v[152:155], v[198:201], v[64:67]
	v_mfma_f32_16x16x32_bf16 v[52:55], v[144:147], v[214:217], v[52:55]
	v_mfma_f32_16x16x32_bf16 v[48:51], v[152:155], v[214:217], v[48:51]
	v_mfma_f32_16x16x32_bf16 v[36:39], v[144:147], v[222:225], v[36:39]
	v_mfma_f32_16x16x32_bf16 v[32:35], v[152:155], v[222:225], v[32:35]
	v_mfma_f32_16x16x32_bf16 v[20:23], v[144:147], v[230:233], v[20:23]
	v_mfma_f32_16x16x32_bf16 v[16:19], v[152:155], v[230:233], v[16:19]
	v_mfma_f32_16x16x32_bf16 v[4:7], v[144:147], v[238:241], v[4:7]
	v_mfma_f32_16x16x32_bf16 v[0:3], v[152:155], v[238:241], v[0:3]
	s_barrier
	s_add_i32 s68, s68, 2
	s_add_u32 s12, s12, 0x100
	s_addc_u32 s13, s13, 0
	s_add_u32 s80, s80, 0x100
	s_addc_u32 s81, s81, 0
	s_add_u32 s82, s82, 0x100
	s_addc_u32 s83, s83, 0
	s_cmp_gt_u32 s68, 41
	s_cbranch_scc0 .LBB0_1140
	s_and_b64 vcc, exec, s[2:3]
	s_cbranch_vccz .LBB0_1143
	s_barrier
